# rwkv scan tile loop rewritten: double-buffered LDS staging overlapped with steps, y reduced in registers via DPP, one barrier per tile
# speedup vs baseline: 1.0424x; 1.0158x over previous
.LBB0_199:
	s_or_b64 exec, exec, s[0:1]
	v_add_u32_e32 v38, v0, v90
	v_ashrrev_i32_e32 v39, 31, v38
	v_lshlrev_b64 v[0:1], 10, v[38:39]
	v_lshl_add_u64 v[0:1], v[32:33], 0, v[0:1]
	v_lshl_add_u64 v[0:1], v[0:1], 0, v[64:65]
	v_lshlrev_b64 v[2:3], 1, v[0:1]
	v_lshl_add_u64 v[4:5], s[8:9], 0, v[2:3]
	v_lshl_add_u64 v[6:7], s[10:11], 0, v[2:3]
	v_lshl_add_u64 v[14:15], s[12:13], 0, v[2:3]
	v_lshl_add_u64 v[16:17], s[14:15], 0, v[2:3]
	global_load_dwordx2 v[40:41], v[4:5], off
	global_load_dwordx2 v[42:43], v[6:7], off
	global_load_dwordx2 v[44:45], v[14:15], off
	global_load_dwordx2 v[46:47], v[16:17], off
	v_add_u32_e32 v4, 16, v38
	v_ashrrev_i32_e32 v5, 31, v4
	v_lshlrev_b64 v[4:5], 10, v[4:5]
	v_lshl_add_u64 v[4:5], v[32:33], 0, v[4:5]
	v_lshl_add_u64 v[4:5], v[4:5], 0, v[64:65]
	v_lshlrev_b64 v[14:15], 1, v[4:5]
	v_lshl_add_u64 v[2:3], s[34:35], 0, v[2:3]
	v_lshl_add_u64 v[0:1], v[0:1], 2, s[36:37]
	v_lshl_add_u64 v[6:7], v[4:5], 2, s[36:37]
	v_lshl_add_u64 v[16:17], s[34:35], 0, v[14:15]
	global_load_dwordx2 v[48:49], v[2:3], off
	s_nop 0
	global_load_dwordx4 v[0:3], v[0:1], off
	s_nop 0
	global_load_dwordx4 v[4:7], v[6:7], off
	s_nop 0
	global_load_dwordx2 v[54:55], v[16:17], off
	v_lshl_add_u64 v[16:17], s[14:15], 0, v[14:15]
	v_lshl_add_u64 v[18:19], s[12:13], 0, v[14:15]
	v_lshl_add_u64 v[20:21], s[10:11], 0, v[14:15]
	v_lshl_add_u64 v[14:15], s[8:9], 0, v[14:15]
	global_load_dwordx2 v[62:63], v[16:17], off
	global_load_dwordx2 v[60:61], v[18:19], off
	global_load_dwordx2 v[58:59], v[20:21], off
	global_load_dwordx2 v[56:57], v[14:15], off
	v_readlane_b32 s0, v254, 27
	v_readlane_b32 s1, v254, 28
	v_lshlrev_b32_e32 v96, 1, v12
	v_mov_b32_e32 v67, v97
	v_lshl_add_u64 v[14:15], v[32:33], 1, s[0:1]
	v_lshl_add_u64 v[12:13], v[14:15], 0, v[96:97]
	v_readlane_b32 s0, v253, 21
	v_lshl_add_u32 v39, v36, 2, 0
	v_lshl_add_u64 v[50:51], v[12:13], 0, v[66:67]
	v_or_b32_e32 v52, v64, v32
	v_mov_b32_e32 v35, v33
	v_lshl_add_u32 v67, v36, 2, s0
	s_mov_b64 s[60:61], 0
	v_and_b32_e32 v177, 15, v176
	v_sub_u32_e32 v178, v38, v90
	v_add_u32_e32 v178, v178, v177
	v_lshlrev_b32_e32 v182, 1, v90
	v_mov_b32_e32 v183, v97
	v_lshl_add_u64 v[180:181], v[12:13], 0, v[182:183]
	v_readfirstlane_b32 s89, v75
	s_mov_b32 s88, 0
	s_waitcnt vmcnt(0)
	v_and_b32_e32 v77, 0xffff0000, v40
	v_lshlrev_b32_e32 v76, 16, v40
	v_and_b32_e32 v79, 0xffff0000, v41
	v_lshlrev_b32_e32 v78, 16, v41
	ds_write_b128 v103, v[76:79]
	v_and_b32_e32 v77, 0xffff0000, v42
	v_lshlrev_b32_e32 v76, 16, v42
	v_and_b32_e32 v79, 0xffff0000, v43
	v_lshlrev_b32_e32 v78, 16, v43
	ds_write_b128 v103, v[76:79] offset:8192
	v_and_b32_e32 v77, 0xffff0000, v44
	v_lshlrev_b32_e32 v76, 16, v44
	v_and_b32_e32 v79, 0xffff0000, v45
	v_lshlrev_b32_e32 v78, 16, v45
	ds_write_b128 v103, v[76:79] offset:12288
	v_and_b32_e32 v77, 0xffff0000, v46
	v_lshlrev_b32_e32 v76, 16, v46
	v_and_b32_e32 v79, 0xffff0000, v47
	v_lshlrev_b32_e32 v78, 16, v47
	ds_write_b128 v103, v[76:79] offset:16384
	v_and_b32_e32 v77, 0xffff0000, v48
	v_lshlrev_b32_e32 v76, 16, v48
	v_and_b32_e32 v79, 0xffff0000, v49
	v_lshlrev_b32_e32 v78, 16, v49
	ds_write_b128 v103, v[76:79] offset:20480
	ds_write_b128 v103, v[0:3] offset:4096
	s_add_i32 s7, s89, -1
	s_min_u32 s6, s7, 2
	v_lshl_add_u32 v122, s6, 4, v38
	v_ashrrev_i32_e32 v123, 31, v122
	v_lshlrev_b64 v[122:123], 10, v[122:123]
	v_or_b32_e32 v123, v123, v35
	v_or_b32_e32 v122, v122, v52
	v_lshlrev_b64 v[124:125], 1, v[122:123]
	v_lshl_add_u64 v[126:127], s[8:9], 0, v[124:125]
	global_load_dwordx2 v[40:41], v[126:127], off
	v_lshl_add_u64 v[128:129], s[10:11], 0, v[124:125]
	global_load_dwordx2 v[42:43], v[128:129], off
	v_lshl_add_u64 v[130:131], s[12:13], 0, v[124:125]
	global_load_dwordx2 v[44:45], v[130:131], off
	v_lshl_add_u64 v[132:133], s[14:15], 0, v[124:125]
	global_load_dwordx2 v[46:47], v[132:133], off
	v_lshl_add_u64 v[124:125], s[34:35], 0, v[124:125]
	global_load_dwordx2 v[48:49], v[124:125], off
	v_lshl_add_u64 v[122:123], v[122:123], 2, s[36:37]
	global_load_dwordx4 v[0:3], v[122:123], off
	s_waitcnt lgkmcnt(0)
	s_barrier
.Lscan_tiles:
	ds_read_b128 v[16:19], v94 offset:12288
	ds_read_b128 v[12:15], v94 offset:8192
	ds_read_b32 v74, v39 offset:20480
	ds_read_b128 v[24:27], v94 offset:4096
	ds_read_b128 v[20:23], v94 offset:16384
	ds_read_b128 v[28:31], v94 offset:0
	s_waitcnt lgkmcnt(3)
	v_pk_mul_f32 v[16:17], v[8:9], v[16:17]
	v_pk_mul_f32 v[12:13], v[12:13], v[74:75] op_sel_hi:[1,0]
	v_pk_fma_f32 v[16:17], v[10:11], v[18:19], v[16:17]
	v_pk_mul_f32 v[14:15], v[14:15], v[74:75] op_sel_hi:[1,0]
	v_add_f32_e32 v16, v16, v17
	s_waitcnt lgkmcnt(2)
	v_pk_fma_f32 v[12:13], v[8:9], v[24:25], v[12:13]
	v_pk_fma_f32 v[14:15], v[10:11], v[26:27], v[14:15]
	v_add_f32_dpp v16, v16, v16 quad_perm:[1,0,3,2] row_mask:0xf bank_mask:0xf bound_ctrl:1
	ds_read_b128 v[84:87], v94 offset:12544
	ds_read_b128 v[80:83], v94 offset:8448
	v_add_f32_dpp v16, v16, v16 quad_perm:[2,3,0,1] row_mask:0xf bank_mask:0xf bound_ctrl:1
	ds_read_b32 v88, v39 offset:20736
	ds_read_b128 v[114:117], v94 offset:4352
	v_add_f32_dpp v16, v16, v16 row_half_mirror row_mask:0xf bank_mask:0xf bound_ctrl:1
	s_nop 1
	v_add_f32_dpp v16, v16, v16 row_mirror row_mask:0xf bank_mask:0xf bound_ctrl:1
	s_waitcnt lgkmcnt(5)
	v_pk_fma_f32 v[8:9], v[20:21], v[16:17], v[12:13] op_sel_hi:[1,0,1] neg_lo:[0,1,0] neg_hi:[0,1,0]
	v_pk_fma_f32 v[10:11], v[22:23], v[16:17], v[14:15] op_sel_hi:[1,0,1] neg_lo:[0,1,0] neg_hi:[0,1,0]
	ds_read_b128 v[110:113], v94 offset:16640
	ds_read_b128 v[118:121], v94 offset:256
	s_waitcnt lgkmcnt(5)
	v_pk_mul_f32 v[84:85], v[8:9], v[84:85]
	v_pk_mul_f32 v[28:29], v[8:9], v[28:29]
	v_pk_fma_f32 v[84:85], v[10:11], v[86:87], v[84:85]
	v_pk_fma_f32 v[28:29], v[10:11], v[30:31], v[28:29]
	v_add_f32_e32 v84, v84, v85
	v_add_f32_e32 v28, v28, v29
	s_waitcnt lgkmcnt(3)
	v_pk_mul_f32 v[80:81], v[80:81], v[88:89] op_sel_hi:[1,0]
	v_pk_mul_f32 v[82:83], v[82:83], v[88:89] op_sel_hi:[1,0]
	v_add_f32_dpp v84, v84, v84 quad_perm:[1,0,3,2] row_mask:0xf bank_mask:0xf bound_ctrl:1
	v_add_f32_dpp v28, v28, v28 quad_perm:[1,0,3,2] row_mask:0xf bank_mask:0xf bound_ctrl:1
	s_waitcnt lgkmcnt(2)
	v_pk_fma_f32 v[80:81], v[8:9], v[114:115], v[80:81]
	v_pk_fma_f32 v[82:83], v[10:11], v[116:117], v[82:83]
	v_add_f32_dpp v84, v84, v84 quad_perm:[2,3,0,1] row_mask:0xf bank_mask:0xf bound_ctrl:1
	v_add_f32_dpp v28, v28, v28 quad_perm:[2,3,0,1] row_mask:0xf bank_mask:0xf bound_ctrl:1
	ds_read_b128 v[16:19], v94 offset:12800
	ds_read_b128 v[12:15], v94 offset:8704
	v_add_f32_dpp v84, v84, v84 row_half_mirror row_mask:0xf bank_mask:0xf bound_ctrl:1
	v_add_f32_dpp v28, v28, v28 row_half_mirror row_mask:0xf bank_mask:0xf bound_ctrl:1
	ds_read_b32 v74, v39 offset:20992
	ds_read_b128 v[24:27], v94 offset:4608
	v_add_f32_dpp v84, v84, v84 row_mirror row_mask:0xf bank_mask:0xf bound_ctrl:1
	v_add_f32_dpp v28, v28, v28 row_mirror row_mask:0xf bank_mask:0xf bound_ctrl:1
	v_cmp_eq_u32_e32 vcc, 0, v177
	s_waitcnt vmcnt(7)
	v_and_b32_e32 v77, 0xffff0000, v56
	v_lshlrev_b32_e32 v76, 16, v56
	v_and_b32_e32 v79, 0xffff0000, v57
	v_lshlrev_b32_e32 v78, 16, v57
	ds_write_b128 v103, v[76:79] offset:24576
	s_waitcnt lgkmcnt(6)
	v_pk_fma_f32 v[8:9], v[110:111], v[84:85], v[80:81] op_sel_hi:[1,0,1] neg_lo:[0,1,0] neg_hi:[0,1,0]
	v_pk_fma_f32 v[10:11], v[112:113], v[84:85], v[82:83] op_sel_hi:[1,0,1] neg_lo:[0,1,0] neg_hi:[0,1,0]
	v_cndmask_b32_e32 v67, v67, v28, vcc
	ds_read_b128 v[20:23], v94 offset:16896
	ds_read_b128 v[28:31], v94 offset:512
	s_waitcnt lgkmcnt(6)
	v_pk_mul_f32 v[16:17], v[8:9], v[16:17]
	v_pk_mul_f32 v[118:119], v[8:9], v[118:119]
	v_pk_fma_f32 v[16:17], v[10:11], v[18:19], v[16:17]
	v_pk_fma_f32 v[118:119], v[10:11], v[120:121], v[118:119]
	v_add_f32_e32 v16, v16, v17
	v_add_f32_e32 v118, v118, v119
	s_waitcnt lgkmcnt(4)
	v_pk_mul_f32 v[12:13], v[12:13], v[74:75] op_sel_hi:[1,0]
	v_pk_mul_f32 v[14:15], v[14:15], v[74:75] op_sel_hi:[1,0]
	v_add_f32_dpp v16, v16, v16 quad_perm:[1,0,3,2] row_mask:0xf bank_mask:0xf bound_ctrl:1
	v_add_f32_dpp v118, v118, v118 quad_perm:[1,0,3,2] row_mask:0xf bank_mask:0xf bound_ctrl:1
	s_waitcnt lgkmcnt(3)
	v_pk_fma_f32 v[12:13], v[8:9], v[24:25], v[12:13]
	v_pk_fma_f32 v[14:15], v[10:11], v[26:27], v[14:15]
	v_add_f32_dpp v16, v16, v16 quad_perm:[2,3,0,1] row_mask:0xf bank_mask:0xf bound_ctrl:1
	v_add_f32_dpp v118, v118, v118 quad_perm:[2,3,0,1] row_mask:0xf bank_mask:0xf bound_ctrl:1
	ds_read_b128 v[84:87], v94 offset:13056
	ds_read_b128 v[80:83], v94 offset:8960
	v_add_f32_dpp v16, v16, v16 row_half_mirror row_mask:0xf bank_mask:0xf bound_ctrl:1
	v_add_f32_dpp v118, v118, v118 row_half_mirror row_mask:0xf bank_mask:0xf bound_ctrl:1
	ds_read_b32 v88, v39 offset:21248
	ds_read_b128 v[114:117], v94 offset:4864
	v_add_f32_dpp v16, v16, v16 row_mirror row_mask:0xf bank_mask:0xf bound_ctrl:1
	v_add_f32_dpp v118, v118, v118 row_mirror row_mask:0xf bank_mask:0xf bound_ctrl:1
	v_cmp_eq_u32_e32 vcc, 1, v177
	v_and_b32_e32 v77, 0xffff0000, v58
	v_lshlrev_b32_e32 v76, 16, v58
	v_and_b32_e32 v79, 0xffff0000, v59
	v_lshlrev_b32_e32 v78, 16, v59
	ds_write_b128 v103, v[76:79] offset:32768
	v_and_b32_e32 v77, 0xffff0000, v60
	s_waitcnt lgkmcnt(6)
	v_pk_fma_f32 v[8:9], v[20:21], v[16:17], v[12:13] op_sel_hi:[1,0,1] neg_lo:[0,1,0] neg_hi:[0,1,0]
	v_pk_fma_f32 v[10:11], v[22:23], v[16:17], v[14:15] op_sel_hi:[1,0,1] neg_lo:[0,1,0] neg_hi:[0,1,0]
	v_cndmask_b32_e32 v67, v67, v118, vcc
	ds_read_b128 v[110:113], v94 offset:17152
	ds_read_b128 v[118:121], v94 offset:768
	s_waitcnt lgkmcnt(6)
	v_pk_mul_f32 v[84:85], v[8:9], v[84:85]
	v_pk_mul_f32 v[28:29], v[8:9], v[28:29]
	v_pk_fma_f32 v[84:85], v[10:11], v[86:87], v[84:85]
	v_pk_fma_f32 v[28:29], v[10:11], v[30:31], v[28:29]
	v_add_f32_e32 v84, v84, v85
	v_add_f32_e32 v28, v28, v29
	s_waitcnt lgkmcnt(4)
	v_pk_mul_f32 v[80:81], v[80:81], v[88:89] op_sel_hi:[1,0]
	v_pk_mul_f32 v[82:83], v[82:83], v[88:89] op_sel_hi:[1,0]
	v_add_f32_dpp v84, v84, v84 quad_perm:[1,0,3,2] row_mask:0xf bank_mask:0xf bound_ctrl:1
	v_add_f32_dpp v28, v28, v28 quad_perm:[1,0,3,2] row_mask:0xf bank_mask:0xf bound_ctrl:1
	s_waitcnt lgkmcnt(3)
	v_pk_fma_f32 v[80:81], v[8:9], v[114:115], v[80:81]
	v_pk_fma_f32 v[82:83], v[10:11], v[116:117], v[82:83]
	v_add_f32_dpp v84, v84, v84 quad_perm:[2,3,0,1] row_mask:0xf bank_mask:0xf bound_ctrl:1
	v_add_f32_dpp v28, v28, v28 quad_perm:[2,3,0,1] row_mask:0xf bank_mask:0xf bound_ctrl:1
	ds_read_b128 v[16:19], v94 offset:13312
	ds_read_b128 v[12:15], v94 offset:9216
	v_add_f32_dpp v84, v84, v84 row_half_mirror row_mask:0xf bank_mask:0xf bound_ctrl:1
	v_add_f32_dpp v28, v28, v28 row_half_mirror row_mask:0xf bank_mask:0xf bound_ctrl:1
	ds_read_b32 v74, v39 offset:21504
	ds_read_b128 v[24:27], v94 offset:5120
	v_add_f32_dpp v84, v84, v84 row_mirror row_mask:0xf bank_mask:0xf bound_ctrl:1
	v_add_f32_dpp v28, v28, v28 row_mirror row_mask:0xf bank_mask:0xf bound_ctrl:1
	v_cmp_eq_u32_e32 vcc, 2, v177
	v_lshlrev_b32_e32 v76, 16, v60
	v_and_b32_e32 v79, 0xffff0000, v61
	v_lshlrev_b32_e32 v78, 16, v61
	ds_write_b128 v103, v[76:79] offset:36864
	v_and_b32_e32 v77, 0xffff0000, v62
	v_lshlrev_b32_e32 v76, 16, v62
	s_waitcnt lgkmcnt(6)
	v_pk_fma_f32 v[8:9], v[110:111], v[84:85], v[80:81] op_sel_hi:[1,0,1] neg_lo:[0,1,0] neg_hi:[0,1,0]
	v_pk_fma_f32 v[10:11], v[112:113], v[84:85], v[82:83] op_sel_hi:[1,0,1] neg_lo:[0,1,0] neg_hi:[0,1,0]
	v_cndmask_b32_e32 v67, v67, v28, vcc
	ds_read_b128 v[20:23], v94 offset:17408
	ds_read_b128 v[28:31], v94 offset:1024
	s_waitcnt lgkmcnt(6)
	v_pk_mul_f32 v[16:17], v[8:9], v[16:17]
	v_pk_mul_f32 v[118:119], v[8:9], v[118:119]
	v_pk_fma_f32 v[16:17], v[10:11], v[18:19], v[16:17]
	v_pk_fma_f32 v[118:119], v[10:11], v[120:121], v[118:119]
	v_add_f32_e32 v16, v16, v17
	v_add_f32_e32 v118, v118, v119
	s_waitcnt lgkmcnt(4)
	v_pk_mul_f32 v[12:13], v[12:13], v[74:75] op_sel_hi:[1,0]
	v_pk_mul_f32 v[14:15], v[14:15], v[74:75] op_sel_hi:[1,0]
	v_add_f32_dpp v16, v16, v16 quad_perm:[1,0,3,2] row_mask:0xf bank_mask:0xf bound_ctrl:1
	v_add_f32_dpp v118, v118, v118 quad_perm:[1,0,3,2] row_mask:0xf bank_mask:0xf bound_ctrl:1
	s_waitcnt lgkmcnt(3)
	v_pk_fma_f32 v[12:13], v[8:9], v[24:25], v[12:13]
	v_pk_fma_f32 v[14:15], v[10:11], v[26:27], v[14:15]
	v_add_f32_dpp v16, v16, v16 quad_perm:[2,3,0,1] row_mask:0xf bank_mask:0xf bound_ctrl:1
	v_add_f32_dpp v118, v118, v118 quad_perm:[2,3,0,1] row_mask:0xf bank_mask:0xf bound_ctrl:1
	ds_read_b128 v[84:87], v94 offset:13568
	ds_read_b128 v[80:83], v94 offset:9472
	v_add_f32_dpp v16, v16, v16 row_half_mirror row_mask:0xf bank_mask:0xf bound_ctrl:1
	v_add_f32_dpp v118, v118, v118 row_half_mirror row_mask:0xf bank_mask:0xf bound_ctrl:1
	ds_read_b32 v88, v39 offset:21760
	ds_read_b128 v[114:117], v94 offset:5376
	v_add_f32_dpp v16, v16, v16 row_mirror row_mask:0xf bank_mask:0xf bound_ctrl:1
	v_add_f32_dpp v118, v118, v118 row_mirror row_mask:0xf bank_mask:0xf bound_ctrl:1
	v_cmp_eq_u32_e32 vcc, 3, v177
	v_and_b32_e32 v79, 0xffff0000, v63
	v_lshlrev_b32_e32 v78, 16, v63
	ds_write_b128 v103, v[76:79] offset:40960
	v_and_b32_e32 v77, 0xffff0000, v54
	v_lshlrev_b32_e32 v76, 16, v54
	v_and_b32_e32 v79, 0xffff0000, v55
	s_waitcnt lgkmcnt(6)
	v_pk_fma_f32 v[8:9], v[20:21], v[16:17], v[12:13] op_sel_hi:[1,0,1] neg_lo:[0,1,0] neg_hi:[0,1,0]
	v_pk_fma_f32 v[10:11], v[22:23], v[16:17], v[14:15] op_sel_hi:[1,0,1] neg_lo:[0,1,0] neg_hi:[0,1,0]
	v_cndmask_b32_e32 v67, v67, v118, vcc
	ds_read_b128 v[110:113], v94 offset:17664
	ds_read_b128 v[118:121], v94 offset:1280
	s_waitcnt lgkmcnt(6)
	v_pk_mul_f32 v[84:85], v[8:9], v[84:85]
	v_pk_mul_f32 v[28:29], v[8:9], v[28:29]
	v_pk_fma_f32 v[84:85], v[10:11], v[86:87], v[84:85]
	v_pk_fma_f32 v[28:29], v[10:11], v[30:31], v[28:29]
	v_add_f32_e32 v84, v84, v85
	v_add_f32_e32 v28, v28, v29
	s_waitcnt lgkmcnt(4)
	v_pk_mul_f32 v[80:81], v[80:81], v[88:89] op_sel_hi:[1,0]
	v_pk_mul_f32 v[82:83], v[82:83], v[88:89] op_sel_hi:[1,0]
	v_add_f32_dpp v84, v84, v84 quad_perm:[1,0,3,2] row_mask:0xf bank_mask:0xf bound_ctrl:1
	v_add_f32_dpp v28, v28, v28 quad_perm:[1,0,3,2] row_mask:0xf bank_mask:0xf bound_ctrl:1
	s_waitcnt lgkmcnt(3)
	v_pk_fma_f32 v[80:81], v[8:9], v[114:115], v[80:81]
	v_pk_fma_f32 v[82:83], v[10:11], v[116:117], v[82:83]
	v_add_f32_dpp v84, v84, v84 quad_perm:[2,3,0,1] row_mask:0xf bank_mask:0xf bound_ctrl:1
	v_add_f32_dpp v28, v28, v28 quad_perm:[2,3,0,1] row_mask:0xf bank_mask:0xf bound_ctrl:1
	ds_read_b128 v[16:19], v94 offset:13824
	ds_read_b128 v[12:15], v94 offset:9728
	v_add_f32_dpp v84, v84, v84 row_half_mirror row_mask:0xf bank_mask:0xf bound_ctrl:1
	v_add_f32_dpp v28, v28, v28 row_half_mirror row_mask:0xf bank_mask:0xf bound_ctrl:1
	ds_read_b32 v74, v39 offset:22016
	ds_read_b128 v[24:27], v94 offset:5632
	v_add_f32_dpp v84, v84, v84 row_mirror row_mask:0xf bank_mask:0xf bound_ctrl:1
	v_add_f32_dpp v28, v28, v28 row_mirror row_mask:0xf bank_mask:0xf bound_ctrl:1
	v_cmp_eq_u32_e32 vcc, 4, v177
	v_lshlrev_b32_e32 v78, 16, v55
	ds_write_b128 v103, v[76:79] offset:45056
	ds_write_b128 v103, v[4:7] offset:28672
	s_add_i32 s6, s88, 3
	s_add_i32 s7, s89, -1
	s_min_u32 s6, s6, s7
	s_waitcnt lgkmcnt(7)
	v_pk_fma_f32 v[8:9], v[110:111], v[84:85], v[80:81] op_sel_hi:[1,0,1] neg_lo:[0,1,0] neg_hi:[0,1,0]
	v_pk_fma_f32 v[10:11], v[112:113], v[84:85], v[82:83] op_sel_hi:[1,0,1] neg_lo:[0,1,0] neg_hi:[0,1,0]
	v_cndmask_b32_e32 v67, v67, v28, vcc
	ds_read_b128 v[20:23], v94 offset:17920
	ds_read_b128 v[28:31], v94 offset:1536
	s_waitcnt lgkmcnt(7)
	v_pk_mul_f32 v[16:17], v[8:9], v[16:17]
	v_pk_mul_f32 v[118:119], v[8:9], v[118:119]
	v_pk_fma_f32 v[16:17], v[10:11], v[18:19], v[16:17]
	v_pk_fma_f32 v[118:119], v[10:11], v[120:121], v[118:119]
	v_add_f32_e32 v16, v16, v17
	v_add_f32_e32 v118, v118, v119
	s_waitcnt lgkmcnt(5)
	v_pk_mul_f32 v[12:13], v[12:13], v[74:75] op_sel_hi:[1,0]
	v_pk_mul_f32 v[14:15], v[14:15], v[74:75] op_sel_hi:[1,0]
	v_add_f32_dpp v16, v16, v16 quad_perm:[1,0,3,2] row_mask:0xf bank_mask:0xf bound_ctrl:1
	v_add_f32_dpp v118, v118, v118 quad_perm:[1,0,3,2] row_mask:0xf bank_mask:0xf bound_ctrl:1
	s_waitcnt lgkmcnt(4)
	v_pk_fma_f32 v[12:13], v[8:9], v[24:25], v[12:13]
	v_pk_fma_f32 v[14:15], v[10:11], v[26:27], v[14:15]
	v_add_f32_dpp v16, v16, v16 quad_perm:[2,3,0,1] row_mask:0xf bank_mask:0xf bound_ctrl:1
	v_add_f32_dpp v118, v118, v118 quad_perm:[2,3,0,1] row_mask:0xf bank_mask:0xf bound_ctrl:1
	ds_read_b128 v[84:87], v94 offset:14080
	ds_read_b128 v[80:83], v94 offset:9984
	v_add_f32_dpp v16, v16, v16 row_half_mirror row_mask:0xf bank_mask:0xf bound_ctrl:1
	v_add_f32_dpp v118, v118, v118 row_half_mirror row_mask:0xf bank_mask:0xf bound_ctrl:1
	ds_read_b32 v88, v39 offset:22272
	ds_read_b128 v[114:117], v94 offset:5888
	v_add_f32_dpp v16, v16, v16 row_mirror row_mask:0xf bank_mask:0xf bound_ctrl:1
	v_add_f32_dpp v118, v118, v118 row_mirror row_mask:0xf bank_mask:0xf bound_ctrl:1
	v_cmp_eq_u32_e32 vcc, 5, v177
	v_lshl_add_u32 v122, s6, 4, v38
	v_ashrrev_i32_e32 v123, 31, v122
	v_lshlrev_b64 v[122:123], 10, v[122:123]
	v_or_b32_e32 v123, v123, v35
	v_or_b32_e32 v122, v122, v52
	v_lshlrev_b64 v[124:125], 1, v[122:123]
	s_waitcnt lgkmcnt(5)
	v_pk_fma_f32 v[8:9], v[20:21], v[16:17], v[12:13] op_sel_hi:[1,0,1] neg_lo:[0,1,0] neg_hi:[0,1,0]
	v_pk_fma_f32 v[10:11], v[22:23], v[16:17], v[14:15] op_sel_hi:[1,0,1] neg_lo:[0,1,0] neg_hi:[0,1,0]
	v_cndmask_b32_e32 v67, v67, v118, vcc
	ds_read_b128 v[110:113], v94 offset:18176
	ds_read_b128 v[118:121], v94 offset:1792
	s_waitcnt lgkmcnt(5)
	v_pk_mul_f32 v[84:85], v[8:9], v[84:85]
	v_pk_mul_f32 v[28:29], v[8:9], v[28:29]
	v_pk_fma_f32 v[84:85], v[10:11], v[86:87], v[84:85]
	v_pk_fma_f32 v[28:29], v[10:11], v[30:31], v[28:29]
	v_add_f32_e32 v84, v84, v85
	v_add_f32_e32 v28, v28, v29
	s_waitcnt lgkmcnt(3)
	v_pk_mul_f32 v[80:81], v[80:81], v[88:89] op_sel_hi:[1,0]
	v_pk_mul_f32 v[82:83], v[82:83], v[88:89] op_sel_hi:[1,0]
	v_add_f32_dpp v84, v84, v84 quad_perm:[1,0,3,2] row_mask:0xf bank_mask:0xf bound_ctrl:1
	v_add_f32_dpp v28, v28, v28 quad_perm:[1,0,3,2] row_mask:0xf bank_mask:0xf bound_ctrl:1
	s_waitcnt lgkmcnt(2)
	v_pk_fma_f32 v[80:81], v[8:9], v[114:115], v[80:81]
	v_pk_fma_f32 v[82:83], v[10:11], v[116:117], v[82:83]
	v_add_f32_dpp v84, v84, v84 quad_perm:[2,3,0,1] row_mask:0xf bank_mask:0xf bound_ctrl:1
	v_add_f32_dpp v28, v28, v28 quad_perm:[2,3,0,1] row_mask:0xf bank_mask:0xf bound_ctrl:1
	ds_read_b128 v[16:19], v94 offset:14336
	ds_read_b128 v[12:15], v94 offset:10240
	v_add_f32_dpp v84, v84, v84 row_half_mirror row_mask:0xf bank_mask:0xf bound_ctrl:1
	v_add_f32_dpp v28, v28, v28 row_half_mirror row_mask:0xf bank_mask:0xf bound_ctrl:1
	ds_read_b32 v74, v39 offset:22528
	ds_read_b128 v[24:27], v94 offset:6144
	v_add_f32_dpp v84, v84, v84 row_mirror row_mask:0xf bank_mask:0xf bound_ctrl:1
	v_add_f32_dpp v28, v28, v28 row_mirror row_mask:0xf bank_mask:0xf bound_ctrl:1
	v_cmp_eq_u32_e32 vcc, 6, v177
	v_lshl_add_u64 v[126:127], s[8:9], 0, v[124:125]
	global_load_dwordx2 v[56:57], v[126:127], off
	v_lshl_add_u64 v[128:129], s[10:11], 0, v[124:125]
	global_load_dwordx2 v[58:59], v[128:129], off
	v_lshl_add_u64 v[130:131], s[12:13], 0, v[124:125]
	global_load_dwordx2 v[60:61], v[130:131], off
	s_waitcnt lgkmcnt(5)
	v_pk_fma_f32 v[8:9], v[110:111], v[84:85], v[80:81] op_sel_hi:[1,0,1] neg_lo:[0,1,0] neg_hi:[0,1,0]
	v_pk_fma_f32 v[10:11], v[112:113], v[84:85], v[82:83] op_sel_hi:[1,0,1] neg_lo:[0,1,0] neg_hi:[0,1,0]
	v_cndmask_b32_e32 v67, v67, v28, vcc
	ds_read_b128 v[20:23], v94 offset:18432
	ds_read_b128 v[28:31], v94 offset:2048
	s_waitcnt lgkmcnt(5)
	v_pk_mul_f32 v[16:17], v[8:9], v[16:17]
	v_pk_mul_f32 v[118:119], v[8:9], v[118:119]
	v_pk_fma_f32 v[16:17], v[10:11], v[18:19], v[16:17]
	v_pk_fma_f32 v[118:119], v[10:11], v[120:121], v[118:119]
	v_add_f32_e32 v16, v16, v17
	v_add_f32_e32 v118, v118, v119
	s_waitcnt lgkmcnt(3)
	v_pk_mul_f32 v[12:13], v[12:13], v[74:75] op_sel_hi:[1,0]
	v_pk_mul_f32 v[14:15], v[14:15], v[74:75] op_sel_hi:[1,0]
	v_add_f32_dpp v16, v16, v16 quad_perm:[1,0,3,2] row_mask:0xf bank_mask:0xf bound_ctrl:1
	v_add_f32_dpp v118, v118, v118 quad_perm:[1,0,3,2] row_mask:0xf bank_mask:0xf bound_ctrl:1
	s_waitcnt lgkmcnt(2)
	v_pk_fma_f32 v[12:13], v[8:9], v[24:25], v[12:13]
	v_pk_fma_f32 v[14:15], v[10:11], v[26:27], v[14:15]
	v_add_f32_dpp v16, v16, v16 quad_perm:[2,3,0,1] row_mask:0xf bank_mask:0xf bound_ctrl:1
	v_add_f32_dpp v118, v118, v118 quad_perm:[2,3,0,1] row_mask:0xf bank_mask:0xf bound_ctrl:1
	ds_read_b128 v[84:87], v94 offset:14592
	ds_read_b128 v[80:83], v94 offset:10496
	v_add_f32_dpp v16, v16, v16 row_half_mirror row_mask:0xf bank_mask:0xf bound_ctrl:1
	v_add_f32_dpp v118, v118, v118 row_half_mirror row_mask:0xf bank_mask:0xf bound_ctrl:1
	ds_read_b32 v88, v39 offset:22784
	ds_read_b128 v[114:117], v94 offset:6400
	v_add_f32_dpp v16, v16, v16 row_mirror row_mask:0xf bank_mask:0xf bound_ctrl:1
	v_add_f32_dpp v118, v118, v118 row_mirror row_mask:0xf bank_mask:0xf bound_ctrl:1
	v_cmp_eq_u32_e32 vcc, 7, v177
	v_lshl_add_u64 v[132:133], s[14:15], 0, v[124:125]
	global_load_dwordx2 v[62:63], v[132:133], off
	v_lshl_add_u64 v[124:125], s[34:35], 0, v[124:125]
	global_load_dwordx2 v[54:55], v[124:125], off
	v_lshl_add_u64 v[122:123], v[122:123], 2, s[36:37]
	global_load_dwordx4 v[4:7], v[122:123], off
	s_waitcnt lgkmcnt(5)
	v_pk_fma_f32 v[8:9], v[20:21], v[16:17], v[12:13] op_sel_hi:[1,0,1] neg_lo:[0,1,0] neg_hi:[0,1,0]
	v_pk_fma_f32 v[10:11], v[22:23], v[16:17], v[14:15] op_sel_hi:[1,0,1] neg_lo:[0,1,0] neg_hi:[0,1,0]
	v_cndmask_b32_e32 v67, v67, v118, vcc
	ds_read_b128 v[110:113], v94 offset:18688
	ds_read_b128 v[118:121], v94 offset:2304
	s_waitcnt lgkmcnt(5)
	v_pk_mul_f32 v[84:85], v[8:9], v[84:85]
	v_pk_mul_f32 v[28:29], v[8:9], v[28:29]
	v_pk_fma_f32 v[84:85], v[10:11], v[86:87], v[84:85]
	v_pk_fma_f32 v[28:29], v[10:11], v[30:31], v[28:29]
	v_add_f32_e32 v84, v84, v85
	v_add_f32_e32 v28, v28, v29
	s_waitcnt lgkmcnt(3)
	v_pk_mul_f32 v[80:81], v[80:81], v[88:89] op_sel_hi:[1,0]
	v_pk_mul_f32 v[82:83], v[82:83], v[88:89] op_sel_hi:[1,0]
	v_add_f32_dpp v84, v84, v84 quad_perm:[1,0,3,2] row_mask:0xf bank_mask:0xf bound_ctrl:1
	v_add_f32_dpp v28, v28, v28 quad_perm:[1,0,3,2] row_mask:0xf bank_mask:0xf bound_ctrl:1
	s_waitcnt lgkmcnt(2)
	v_pk_fma_f32 v[80:81], v[8:9], v[114:115], v[80:81]
	v_pk_fma_f32 v[82:83], v[10:11], v[116:117], v[82:83]
	v_add_f32_dpp v84, v84, v84 quad_perm:[2,3,0,1] row_mask:0xf bank_mask:0xf bound_ctrl:1
	v_add_f32_dpp v28, v28, v28 quad_perm:[2,3,0,1] row_mask:0xf bank_mask:0xf bound_ctrl:1
	ds_read_b128 v[16:19], v94 offset:14848
	ds_read_b128 v[12:15], v94 offset:10752
	v_add_f32_dpp v84, v84, v84 row_half_mirror row_mask:0xf bank_mask:0xf bound_ctrl:1
	v_add_f32_dpp v28, v28, v28 row_half_mirror row_mask:0xf bank_mask:0xf bound_ctrl:1
	ds_read_b32 v74, v39 offset:23040
	ds_read_b128 v[24:27], v94 offset:6656
	v_add_f32_dpp v84, v84, v84 row_mirror row_mask:0xf bank_mask:0xf bound_ctrl:1
	v_add_f32_dpp v28, v28, v28 row_mirror row_mask:0xf bank_mask:0xf bound_ctrl:1
	v_cmp_eq_u32_e32 vcc, 8, v177
	s_waitcnt lgkmcnt(5)
	v_pk_fma_f32 v[8:9], v[110:111], v[84:85], v[80:81] op_sel_hi:[1,0,1] neg_lo:[0,1,0] neg_hi:[0,1,0]
	v_pk_fma_f32 v[10:11], v[112:113], v[84:85], v[82:83] op_sel_hi:[1,0,1] neg_lo:[0,1,0] neg_hi:[0,1,0]
	v_cndmask_b32_e32 v67, v67, v28, vcc
	ds_read_b128 v[20:23], v94 offset:18944
	ds_read_b128 v[28:31], v94 offset:2560
	s_waitcnt lgkmcnt(5)
	v_pk_mul_f32 v[16:17], v[8:9], v[16:17]
	v_pk_mul_f32 v[118:119], v[8:9], v[118:119]
	v_pk_fma_f32 v[16:17], v[10:11], v[18:19], v[16:17]
	v_pk_fma_f32 v[118:119], v[10:11], v[120:121], v[118:119]
	v_add_f32_e32 v16, v16, v17
	v_add_f32_e32 v118, v118, v119
	s_waitcnt lgkmcnt(3)
	v_pk_mul_f32 v[12:13], v[12:13], v[74:75] op_sel_hi:[1,0]
	v_pk_mul_f32 v[14:15], v[14:15], v[74:75] op_sel_hi:[1,0]
	v_add_f32_dpp v16, v16, v16 quad_perm:[1,0,3,2] row_mask:0xf bank_mask:0xf bound_ctrl:1
	v_add_f32_dpp v118, v118, v118 quad_perm:[1,0,3,2] row_mask:0xf bank_mask:0xf bound_ctrl:1
	s_waitcnt lgkmcnt(2)
	v_pk_fma_f32 v[12:13], v[8:9], v[24:25], v[12:13]
	v_pk_fma_f32 v[14:15], v[10:11], v[26:27], v[14:15]
	v_add_f32_dpp v16, v16, v16 quad_perm:[2,3,0,1] row_mask:0xf bank_mask:0xf bound_ctrl:1
	v_add_f32_dpp v118, v118, v118 quad_perm:[2,3,0,1] row_mask:0xf bank_mask:0xf bound_ctrl:1
	ds_read_b128 v[84:87], v94 offset:15104
	ds_read_b128 v[80:83], v94 offset:11008
	v_add_f32_dpp v16, v16, v16 row_half_mirror row_mask:0xf bank_mask:0xf bound_ctrl:1
	v_add_f32_dpp v118, v118, v118 row_half_mirror row_mask:0xf bank_mask:0xf bound_ctrl:1
	ds_read_b32 v88, v39 offset:23296
	ds_read_b128 v[114:117], v94 offset:6912
	v_add_f32_dpp v16, v16, v16 row_mirror row_mask:0xf bank_mask:0xf bound_ctrl:1
	v_add_f32_dpp v118, v118, v118 row_mirror row_mask:0xf bank_mask:0xf bound_ctrl:1
	v_cmp_eq_u32_e32 vcc, 9, v177
	s_waitcnt lgkmcnt(5)
	v_pk_fma_f32 v[8:9], v[20:21], v[16:17], v[12:13] op_sel_hi:[1,0,1] neg_lo:[0,1,0] neg_hi:[0,1,0]
	v_pk_fma_f32 v[10:11], v[22:23], v[16:17], v[14:15] op_sel_hi:[1,0,1] neg_lo:[0,1,0] neg_hi:[0,1,0]
	v_cndmask_b32_e32 v67, v67, v118, vcc
	ds_read_b128 v[110:113], v94 offset:19200
	ds_read_b128 v[118:121], v94 offset:2816
	s_waitcnt lgkmcnt(5)
	v_pk_mul_f32 v[84:85], v[8:9], v[84:85]
	v_pk_mul_f32 v[28:29], v[8:9], v[28:29]
	v_pk_fma_f32 v[84:85], v[10:11], v[86:87], v[84:85]
	v_pk_fma_f32 v[28:29], v[10:11], v[30:31], v[28:29]
	v_add_f32_e32 v84, v84, v85
	v_add_f32_e32 v28, v28, v29
	s_waitcnt lgkmcnt(3)
	v_pk_mul_f32 v[80:81], v[80:81], v[88:89] op_sel_hi:[1,0]
	v_pk_mul_f32 v[82:83], v[82:83], v[88:89] op_sel_hi:[1,0]
	v_add_f32_dpp v84, v84, v84 quad_perm:[1,0,3,2] row_mask:0xf bank_mask:0xf bound_ctrl:1
	v_add_f32_dpp v28, v28, v28 quad_perm:[1,0,3,2] row_mask:0xf bank_mask:0xf bound_ctrl:1
	s_waitcnt lgkmcnt(2)
	v_pk_fma_f32 v[80:81], v[8:9], v[114:115], v[80:81]
	v_pk_fma_f32 v[82:83], v[10:11], v[116:117], v[82:83]
	v_add_f32_dpp v84, v84, v84 quad_perm:[2,3,0,1] row_mask:0xf bank_mask:0xf bound_ctrl:1
	v_add_f32_dpp v28, v28, v28 quad_perm:[2,3,0,1] row_mask:0xf bank_mask:0xf bound_ctrl:1
	ds_read_b128 v[16:19], v94 offset:15360
	ds_read_b128 v[12:15], v94 offset:11264
	v_add_f32_dpp v84, v84, v84 row_half_mirror row_mask:0xf bank_mask:0xf bound_ctrl:1
	v_add_f32_dpp v28, v28, v28 row_half_mirror row_mask:0xf bank_mask:0xf bound_ctrl:1
	ds_read_b32 v74, v39 offset:23552
	ds_read_b128 v[24:27], v94 offset:7168
	v_add_f32_dpp v84, v84, v84 row_mirror row_mask:0xf bank_mask:0xf bound_ctrl:1
	v_add_f32_dpp v28, v28, v28 row_mirror row_mask:0xf bank_mask:0xf bound_ctrl:1
	v_cmp_eq_u32_e32 vcc, 10, v177
	s_waitcnt lgkmcnt(5)
	v_pk_fma_f32 v[8:9], v[110:111], v[84:85], v[80:81] op_sel_hi:[1,0,1] neg_lo:[0,1,0] neg_hi:[0,1,0]
	v_pk_fma_f32 v[10:11], v[112:113], v[84:85], v[82:83] op_sel_hi:[1,0,1] neg_lo:[0,1,0] neg_hi:[0,1,0]
	v_cndmask_b32_e32 v67, v67, v28, vcc
	ds_read_b128 v[20:23], v94 offset:19456
	ds_read_b128 v[28:31], v94 offset:3072
	s_waitcnt lgkmcnt(5)
	v_pk_mul_f32 v[16:17], v[8:9], v[16:17]
	v_pk_mul_f32 v[118:119], v[8:9], v[118:119]
	v_pk_fma_f32 v[16:17], v[10:11], v[18:19], v[16:17]
	v_pk_fma_f32 v[118:119], v[10:11], v[120:121], v[118:119]
	v_add_f32_e32 v16, v16, v17
	v_add_f32_e32 v118, v118, v119
	s_waitcnt lgkmcnt(3)
	v_pk_mul_f32 v[12:13], v[12:13], v[74:75] op_sel_hi:[1,0]
	v_pk_mul_f32 v[14:15], v[14:15], v[74:75] op_sel_hi:[1,0]
	v_add_f32_dpp v16, v16, v16 quad_perm:[1,0,3,2] row_mask:0xf bank_mask:0xf bound_ctrl:1
	v_add_f32_dpp v118, v118, v118 quad_perm:[1,0,3,2] row_mask:0xf bank_mask:0xf bound_ctrl:1
	s_waitcnt lgkmcnt(2)
	v_pk_fma_f32 v[12:13], v[8:9], v[24:25], v[12:13]
	v_pk_fma_f32 v[14:15], v[10:11], v[26:27], v[14:15]
	v_add_f32_dpp v16, v16, v16 quad_perm:[2,3,0,1] row_mask:0xf bank_mask:0xf bound_ctrl:1
	v_add_f32_dpp v118, v118, v118 quad_perm:[2,3,0,1] row_mask:0xf bank_mask:0xf bound_ctrl:1
	ds_read_b128 v[84:87], v94 offset:15616
	ds_read_b128 v[80:83], v94 offset:11520
	v_add_f32_dpp v16, v16, v16 row_half_mirror row_mask:0xf bank_mask:0xf bound_ctrl:1
	v_add_f32_dpp v118, v118, v118 row_half_mirror row_mask:0xf bank_mask:0xf bound_ctrl:1
	ds_read_b32 v88, v39 offset:23808
	ds_read_b128 v[114:117], v94 offset:7424
	v_add_f32_dpp v16, v16, v16 row_mirror row_mask:0xf bank_mask:0xf bound_ctrl:1
	v_add_f32_dpp v118, v118, v118 row_mirror row_mask:0xf bank_mask:0xf bound_ctrl:1
	v_cmp_eq_u32_e32 vcc, 11, v177
	s_waitcnt lgkmcnt(5)
	v_pk_fma_f32 v[8:9], v[20:21], v[16:17], v[12:13] op_sel_hi:[1,0,1] neg_lo:[0,1,0] neg_hi:[0,1,0]
	v_pk_fma_f32 v[10:11], v[22:23], v[16:17], v[14:15] op_sel_hi:[1,0,1] neg_lo:[0,1,0] neg_hi:[0,1,0]
	v_cndmask_b32_e32 v67, v67, v118, vcc
	ds_read_b128 v[110:113], v94 offset:19712
	ds_read_b128 v[118:121], v94 offset:3328
	s_waitcnt lgkmcnt(5)
	v_pk_mul_f32 v[84:85], v[8:9], v[84:85]
	v_pk_mul_f32 v[28:29], v[8:9], v[28:29]
	v_pk_fma_f32 v[84:85], v[10:11], v[86:87], v[84:85]
	v_pk_fma_f32 v[28:29], v[10:11], v[30:31], v[28:29]
	v_add_f32_e32 v84, v84, v85
	v_add_f32_e32 v28, v28, v29
	s_waitcnt lgkmcnt(3)
	v_pk_mul_f32 v[80:81], v[80:81], v[88:89] op_sel_hi:[1,0]
	v_pk_mul_f32 v[82:83], v[82:83], v[88:89] op_sel_hi:[1,0]
	v_add_f32_dpp v84, v84, v84 quad_perm:[1,0,3,2] row_mask:0xf bank_mask:0xf bound_ctrl:1
	v_add_f32_dpp v28, v28, v28 quad_perm:[1,0,3,2] row_mask:0xf bank_mask:0xf bound_ctrl:1
	s_waitcnt lgkmcnt(2)
	v_pk_fma_f32 v[80:81], v[8:9], v[114:115], v[80:81]
	v_pk_fma_f32 v[82:83], v[10:11], v[116:117], v[82:83]
	v_add_f32_dpp v84, v84, v84 quad_perm:[2,3,0,1] row_mask:0xf bank_mask:0xf bound_ctrl:1
	v_add_f32_dpp v28, v28, v28 quad_perm:[2,3,0,1] row_mask:0xf bank_mask:0xf bound_ctrl:1
	ds_read_b128 v[16:19], v94 offset:15872
	ds_read_b128 v[12:15], v94 offset:11776
	v_add_f32_dpp v84, v84, v84 row_half_mirror row_mask:0xf bank_mask:0xf bound_ctrl:1
	v_add_f32_dpp v28, v28, v28 row_half_mirror row_mask:0xf bank_mask:0xf bound_ctrl:1
	ds_read_b32 v74, v39 offset:24064
	ds_read_b128 v[24:27], v94 offset:7680
	v_add_f32_dpp v84, v84, v84 row_mirror row_mask:0xf bank_mask:0xf bound_ctrl:1
	v_add_f32_dpp v28, v28, v28 row_mirror row_mask:0xf bank_mask:0xf bound_ctrl:1
	v_cmp_eq_u32_e32 vcc, 12, v177
	s_waitcnt lgkmcnt(5)
	v_pk_fma_f32 v[8:9], v[110:111], v[84:85], v[80:81] op_sel_hi:[1,0,1] neg_lo:[0,1,0] neg_hi:[0,1,0]
	v_pk_fma_f32 v[10:11], v[112:113], v[84:85], v[82:83] op_sel_hi:[1,0,1] neg_lo:[0,1,0] neg_hi:[0,1,0]
	v_cndmask_b32_e32 v67, v67, v28, vcc
	ds_read_b128 v[20:23], v94 offset:19968
	ds_read_b128 v[28:31], v94 offset:3584
	s_waitcnt lgkmcnt(5)
	v_pk_mul_f32 v[16:17], v[8:9], v[16:17]
	v_pk_mul_f32 v[118:119], v[8:9], v[118:119]
	v_pk_fma_f32 v[16:17], v[10:11], v[18:19], v[16:17]
	v_pk_fma_f32 v[118:119], v[10:11], v[120:121], v[118:119]
	v_add_f32_e32 v16, v16, v17
	v_add_f32_e32 v118, v118, v119
	s_waitcnt lgkmcnt(3)
	v_pk_mul_f32 v[12:13], v[12:13], v[74:75] op_sel_hi:[1,0]
	v_pk_mul_f32 v[14:15], v[14:15], v[74:75] op_sel_hi:[1,0]
	v_add_f32_dpp v16, v16, v16 quad_perm:[1,0,3,2] row_mask:0xf bank_mask:0xf bound_ctrl:1
	v_add_f32_dpp v118, v118, v118 quad_perm:[1,0,3,2] row_mask:0xf bank_mask:0xf bound_ctrl:1
	s_waitcnt lgkmcnt(2)
	v_pk_fma_f32 v[12:13], v[8:9], v[24:25], v[12:13]
	v_pk_fma_f32 v[14:15], v[10:11], v[26:27], v[14:15]
	v_add_f32_dpp v16, v16, v16 quad_perm:[2,3,0,1] row_mask:0xf bank_mask:0xf bound_ctrl:1
	v_add_f32_dpp v118, v118, v118 quad_perm:[2,3,0,1] row_mask:0xf bank_mask:0xf bound_ctrl:1
	ds_read_b128 v[84:87], v94 offset:16128
	ds_read_b128 v[80:83], v94 offset:12032
	v_add_f32_dpp v16, v16, v16 row_half_mirror row_mask:0xf bank_mask:0xf bound_ctrl:1
	v_add_f32_dpp v118, v118, v118 row_half_mirror row_mask:0xf bank_mask:0xf bound_ctrl:1
	ds_read_b32 v88, v39 offset:24320
	ds_read_b128 v[114:117], v94 offset:7936
	v_add_f32_dpp v16, v16, v16 row_mirror row_mask:0xf bank_mask:0xf bound_ctrl:1
	v_add_f32_dpp v118, v118, v118 row_mirror row_mask:0xf bank_mask:0xf bound_ctrl:1
	v_cmp_eq_u32_e32 vcc, 13, v177
	s_waitcnt lgkmcnt(5)
	v_pk_fma_f32 v[8:9], v[20:21], v[16:17], v[12:13] op_sel_hi:[1,0,1] neg_lo:[0,1,0] neg_hi:[0,1,0]
	v_pk_fma_f32 v[10:11], v[22:23], v[16:17], v[14:15] op_sel_hi:[1,0,1] neg_lo:[0,1,0] neg_hi:[0,1,0]
	v_cndmask_b32_e32 v67, v67, v118, vcc
	ds_read_b128 v[110:113], v94 offset:20224
	ds_read_b128 v[118:121], v94 offset:3840
	s_waitcnt lgkmcnt(5)
	v_pk_mul_f32 v[84:85], v[8:9], v[84:85]
	v_pk_mul_f32 v[28:29], v[8:9], v[28:29]
	v_pk_fma_f32 v[84:85], v[10:11], v[86:87], v[84:85]
	v_pk_fma_f32 v[28:29], v[10:11], v[30:31], v[28:29]
	v_add_f32_e32 v84, v84, v85
	v_add_f32_e32 v28, v28, v29
	s_waitcnt lgkmcnt(3)
	v_pk_mul_f32 v[80:81], v[80:81], v[88:89] op_sel_hi:[1,0]
	v_pk_mul_f32 v[82:83], v[82:83], v[88:89] op_sel_hi:[1,0]
	v_add_f32_dpp v84, v84, v84 quad_perm:[1,0,3,2] row_mask:0xf bank_mask:0xf bound_ctrl:1
	v_add_f32_dpp v28, v28, v28 quad_perm:[1,0,3,2] row_mask:0xf bank_mask:0xf bound_ctrl:1
	s_waitcnt lgkmcnt(2)
	v_pk_fma_f32 v[80:81], v[8:9], v[114:115], v[80:81]
	v_pk_fma_f32 v[82:83], v[10:11], v[116:117], v[82:83]
	v_add_f32_dpp v84, v84, v84 quad_perm:[2,3,0,1] row_mask:0xf bank_mask:0xf bound_ctrl:1
	v_add_f32_dpp v28, v28, v28 quad_perm:[2,3,0,1] row_mask:0xf bank_mask:0xf bound_ctrl:1
	s_nop 1
	v_add_f32_dpp v84, v84, v84 row_half_mirror row_mask:0xf bank_mask:0xf bound_ctrl:1
	v_add_f32_dpp v28, v28, v28 row_half_mirror row_mask:0xf bank_mask:0xf bound_ctrl:1
	s_nop 1
	v_add_f32_dpp v84, v84, v84 row_mirror row_mask:0xf bank_mask:0xf bound_ctrl:1
	v_add_f32_dpp v28, v28, v28 row_mirror row_mask:0xf bank_mask:0xf bound_ctrl:1
	v_cmp_eq_u32_e32 vcc, 14, v177
	s_waitcnt lgkmcnt(1)
	v_pk_fma_f32 v[8:9], v[110:111], v[84:85], v[80:81] op_sel_hi:[1,0,1] neg_lo:[0,1,0] neg_hi:[0,1,0]
	v_pk_fma_f32 v[10:11], v[112:113], v[84:85], v[82:83] op_sel_hi:[1,0,1] neg_lo:[0,1,0] neg_hi:[0,1,0]
	v_cndmask_b32_e32 v67, v67, v28, vcc
	s_waitcnt lgkmcnt(0)
	v_pk_mul_f32 v[118:119], v[8:9], v[118:119]
	s_nop 0
	v_pk_fma_f32 v[118:119], v[10:11], v[120:121], v[118:119]
	s_add_i32 s6, s88, 0
	v_add_f32_e32 v118, v118, v119
	v_lshl_add_u32 v78, s6, 4, v178
	v_ashrrev_i32_e32 v79, 31, v78
	v_add_f32_dpp v118, v118, v118 quad_perm:[1,0,3,2] row_mask:0xf bank_mask:0xf bound_ctrl:1
	v_lshlrev_b64 v[78:79], 11, v[78:79]
	v_cmp_eq_u32_e32 vcc, 15, v177
	v_add_f32_dpp v118, v118, v118 quad_perm:[2,3,0,1] row_mask:0xf bank_mask:0xf bound_ctrl:1
	v_lshl_add_u64 v[78:79], v[180:181], 0, v[78:79]
	s_nop 0
	v_add_f32_dpp v118, v118, v118 row_half_mirror row_mask:0xf bank_mask:0xf bound_ctrl:1
	s_nop 1
	v_add_f32_dpp v118, v118, v118 row_mirror row_mask:0xf bank_mask:0xf bound_ctrl:1
	s_nop 0
	v_cndmask_b32_e32 v67, v67, v118, vcc
	v_bfe_u32 v76, v67, 16, 1
	v_add3_u32 v76, v67, v76, s33
	global_store_short_d16_hi v[78:79], v76, off
	s_waitcnt lgkmcnt(0)
	s_barrier
	s_add_i32 s6, s88, 1
	s_cmp_ge_u32 s6, s89
	s_cbranch_scc1 .Lscan_tiles_done
	ds_read_b128 v[16:19], v94 offset:36864
	ds_read_b128 v[12:15], v94 offset:32768
	ds_read_b32 v74, v39 offset:45056
	ds_read_b128 v[24:27], v94 offset:28672
	ds_read_b128 v[20:23], v94 offset:40960
	ds_read_b128 v[28:31], v94 offset:24576
	s_waitcnt lgkmcnt(3)
	v_pk_mul_f32 v[16:17], v[8:9], v[16:17]
	v_pk_mul_f32 v[12:13], v[12:13], v[74:75] op_sel_hi:[1,0]
	v_pk_fma_f32 v[16:17], v[10:11], v[18:19], v[16:17]
	v_pk_mul_f32 v[14:15], v[14:15], v[74:75] op_sel_hi:[1,0]
	v_add_f32_e32 v16, v16, v17
	s_waitcnt lgkmcnt(2)
	v_pk_fma_f32 v[12:13], v[8:9], v[24:25], v[12:13]
	v_pk_fma_f32 v[14:15], v[10:11], v[26:27], v[14:15]
	v_add_f32_dpp v16, v16, v16 quad_perm:[1,0,3,2] row_mask:0xf bank_mask:0xf bound_ctrl:1
	ds_read_b128 v[84:87], v94 offset:37120
	ds_read_b128 v[80:83], v94 offset:33024
	v_add_f32_dpp v16, v16, v16 quad_perm:[2,3,0,1] row_mask:0xf bank_mask:0xf bound_ctrl:1
	ds_read_b32 v88, v39 offset:45312
	ds_read_b128 v[114:117], v94 offset:28928
	v_add_f32_dpp v16, v16, v16 row_half_mirror row_mask:0xf bank_mask:0xf bound_ctrl:1
	s_nop 1
	v_add_f32_dpp v16, v16, v16 row_mirror row_mask:0xf bank_mask:0xf bound_ctrl:1
	s_waitcnt lgkmcnt(5)
	v_pk_fma_f32 v[8:9], v[20:21], v[16:17], v[12:13] op_sel_hi:[1,0,1] neg_lo:[0,1,0] neg_hi:[0,1,0]
	v_pk_fma_f32 v[10:11], v[22:23], v[16:17], v[14:15] op_sel_hi:[1,0,1] neg_lo:[0,1,0] neg_hi:[0,1,0]
	ds_read_b128 v[110:113], v94 offset:41216
	ds_read_b128 v[118:121], v94 offset:24832
	s_waitcnt lgkmcnt(5)
	v_pk_mul_f32 v[84:85], v[8:9], v[84:85]
	v_pk_mul_f32 v[28:29], v[8:9], v[28:29]
	v_pk_fma_f32 v[84:85], v[10:11], v[86:87], v[84:85]
	v_pk_fma_f32 v[28:29], v[10:11], v[30:31], v[28:29]
	v_add_f32_e32 v84, v84, v85
	v_add_f32_e32 v28, v28, v29
	s_waitcnt lgkmcnt(3)
	v_pk_mul_f32 v[80:81], v[80:81], v[88:89] op_sel_hi:[1,0]
	v_pk_mul_f32 v[82:83], v[82:83], v[88:89] op_sel_hi:[1,0]
	v_add_f32_dpp v84, v84, v84 quad_perm:[1,0,3,2] row_mask:0xf bank_mask:0xf bound_ctrl:1
	v_add_f32_dpp v28, v28, v28 quad_perm:[1,0,3,2] row_mask:0xf bank_mask:0xf bound_ctrl:1
	s_waitcnt lgkmcnt(2)
	v_pk_fma_f32 v[80:81], v[8:9], v[114:115], v[80:81]
	v_pk_fma_f32 v[82:83], v[10:11], v[116:117], v[82:83]
	v_add_f32_dpp v84, v84, v84 quad_perm:[2,3,0,1] row_mask:0xf bank_mask:0xf bound_ctrl:1
	v_add_f32_dpp v28, v28, v28 quad_perm:[2,3,0,1] row_mask:0xf bank_mask:0xf bound_ctrl:1
	ds_read_b128 v[16:19], v94 offset:37376
	ds_read_b128 v[12:15], v94 offset:33280
	v_add_f32_dpp v84, v84, v84 row_half_mirror row_mask:0xf bank_mask:0xf bound_ctrl:1
	v_add_f32_dpp v28, v28, v28 row_half_mirror row_mask:0xf bank_mask:0xf bound_ctrl:1
	ds_read_b32 v74, v39 offset:45568
	ds_read_b128 v[24:27], v94 offset:29184
	v_add_f32_dpp v84, v84, v84 row_mirror row_mask:0xf bank_mask:0xf bound_ctrl:1
	v_add_f32_dpp v28, v28, v28 row_mirror row_mask:0xf bank_mask:0xf bound_ctrl:1
	v_cmp_eq_u32_e32 vcc, 0, v177
	s_waitcnt vmcnt(7)
	v_and_b32_e32 v77, 0xffff0000, v40
	v_lshlrev_b32_e32 v76, 16, v40
	v_and_b32_e32 v79, 0xffff0000, v41
	v_lshlrev_b32_e32 v78, 16, v41
	ds_write_b128 v103, v[76:79]
	s_waitcnt lgkmcnt(6)
	v_pk_fma_f32 v[8:9], v[110:111], v[84:85], v[80:81] op_sel_hi:[1,0,1] neg_lo:[0,1,0] neg_hi:[0,1,0]
	v_pk_fma_f32 v[10:11], v[112:113], v[84:85], v[82:83] op_sel_hi:[1,0,1] neg_lo:[0,1,0] neg_hi:[0,1,0]
	v_cndmask_b32_e32 v67, v67, v28, vcc
	ds_read_b128 v[20:23], v94 offset:41472
	ds_read_b128 v[28:31], v94 offset:25088
	s_waitcnt lgkmcnt(6)
	v_pk_mul_f32 v[16:17], v[8:9], v[16:17]
	v_pk_mul_f32 v[118:119], v[8:9], v[118:119]
	v_pk_fma_f32 v[16:17], v[10:11], v[18:19], v[16:17]
	v_pk_fma_f32 v[118:119], v[10:11], v[120:121], v[118:119]
	v_add_f32_e32 v16, v16, v17
	v_add_f32_e32 v118, v118, v119
	s_waitcnt lgkmcnt(4)
	v_pk_mul_f32 v[12:13], v[12:13], v[74:75] op_sel_hi:[1,0]
	v_pk_mul_f32 v[14:15], v[14:15], v[74:75] op_sel_hi:[1,0]
	v_add_f32_dpp v16, v16, v16 quad_perm:[1,0,3,2] row_mask:0xf bank_mask:0xf bound_ctrl:1
	v_add_f32_dpp v118, v118, v118 quad_perm:[1,0,3,2] row_mask:0xf bank_mask:0xf bound_ctrl:1
	s_waitcnt lgkmcnt(3)
	v_pk_fma_f32 v[12:13], v[8:9], v[24:25], v[12:13]
	v_pk_fma_f32 v[14:15], v[10:11], v[26:27], v[14:15]
	v_add_f32_dpp v16, v16, v16 quad_perm:[2,3,0,1] row_mask:0xf bank_mask:0xf bound_ctrl:1
	v_add_f32_dpp v118, v118, v118 quad_perm:[2,3,0,1] row_mask:0xf bank_mask:0xf bound_ctrl:1
	ds_read_b128 v[84:87], v94 offset:37632
	ds_read_b128 v[80:83], v94 offset:33536
	v_add_f32_dpp v16, v16, v16 row_half_mirror row_mask:0xf bank_mask:0xf bound_ctrl:1
	v_add_f32_dpp v118, v118, v118 row_half_mirror row_mask:0xf bank_mask:0xf bound_ctrl:1
	ds_read_b32 v88, v39 offset:45824
	ds_read_b128 v[114:117], v94 offset:29440
	v_add_f32_dpp v16, v16, v16 row_mirror row_mask:0xf bank_mask:0xf bound_ctrl:1
	v_add_f32_dpp v118, v118, v118 row_mirror row_mask:0xf bank_mask:0xf bound_ctrl:1
	v_cmp_eq_u32_e32 vcc, 1, v177
	v_and_b32_e32 v77, 0xffff0000, v42
	v_lshlrev_b32_e32 v76, 16, v42
	v_and_b32_e32 v79, 0xffff0000, v43
	v_lshlrev_b32_e32 v78, 16, v43
	ds_write_b128 v103, v[76:79] offset:8192
	v_and_b32_e32 v77, 0xffff0000, v44
	s_waitcnt lgkmcnt(6)
	v_pk_fma_f32 v[8:9], v[20:21], v[16:17], v[12:13] op_sel_hi:[1,0,1] neg_lo:[0,1,0] neg_hi:[0,1,0]
	v_pk_fma_f32 v[10:11], v[22:23], v[16:17], v[14:15] op_sel_hi:[1,0,1] neg_lo:[0,1,0] neg_hi:[0,1,0]
	v_cndmask_b32_e32 v67, v67, v118, vcc
	ds_read_b128 v[110:113], v94 offset:41728
	ds_read_b128 v[118:121], v94 offset:25344
	s_waitcnt lgkmcnt(6)
	v_pk_mul_f32 v[84:85], v[8:9], v[84:85]
	v_pk_mul_f32 v[28:29], v[8:9], v[28:29]
	v_pk_fma_f32 v[84:85], v[10:11], v[86:87], v[84:85]
	v_pk_fma_f32 v[28:29], v[10:11], v[30:31], v[28:29]
	v_add_f32_e32 v84, v84, v85
	v_add_f32_e32 v28, v28, v29
	s_waitcnt lgkmcnt(4)
	v_pk_mul_f32 v[80:81], v[80:81], v[88:89] op_sel_hi:[1,0]
	v_pk_mul_f32 v[82:83], v[82:83], v[88:89] op_sel_hi:[1,0]
	v_add_f32_dpp v84, v84, v84 quad_perm:[1,0,3,2] row_mask:0xf bank_mask:0xf bound_ctrl:1
	v_add_f32_dpp v28, v28, v28 quad_perm:[1,0,3,2] row_mask:0xf bank_mask:0xf bound_ctrl:1
	s_waitcnt lgkmcnt(3)
	v_pk_fma_f32 v[80:81], v[8:9], v[114:115], v[80:81]
	v_pk_fma_f32 v[82:83], v[10:11], v[116:117], v[82:83]
	v_add_f32_dpp v84, v84, v84 quad_perm:[2,3,0,1] row_mask:0xf bank_mask:0xf bound_ctrl:1
	v_add_f32_dpp v28, v28, v28 quad_perm:[2,3,0,1] row_mask:0xf bank_mask:0xf bound_ctrl:1
	ds_read_b128 v[16:19], v94 offset:37888
	ds_read_b128 v[12:15], v94 offset:33792
	v_add_f32_dpp v84, v84, v84 row_half_mirror row_mask:0xf bank_mask:0xf bound_ctrl:1
	v_add_f32_dpp v28, v28, v28 row_half_mirror row_mask:0xf bank_mask:0xf bound_ctrl:1
	ds_read_b32 v74, v39 offset:46080
	ds_read_b128 v[24:27], v94 offset:29696
	v_add_f32_dpp v84, v84, v84 row_mirror row_mask:0xf bank_mask:0xf bound_ctrl:1
	v_add_f32_dpp v28, v28, v28 row_mirror row_mask:0xf bank_mask:0xf bound_ctrl:1
	v_cmp_eq_u32_e32 vcc, 2, v177
	v_lshlrev_b32_e32 v76, 16, v44
	v_and_b32_e32 v79, 0xffff0000, v45
	v_lshlrev_b32_e32 v78, 16, v45
	ds_write_b128 v103, v[76:79] offset:12288
	v_and_b32_e32 v77, 0xffff0000, v46
	v_lshlrev_b32_e32 v76, 16, v46
	s_waitcnt lgkmcnt(6)
	v_pk_fma_f32 v[8:9], v[110:111], v[84:85], v[80:81] op_sel_hi:[1,0,1] neg_lo:[0,1,0] neg_hi:[0,1,0]
	v_pk_fma_f32 v[10:11], v[112:113], v[84:85], v[82:83] op_sel_hi:[1,0,1] neg_lo:[0,1,0] neg_hi:[0,1,0]
	v_cndmask_b32_e32 v67, v67, v28, vcc
	ds_read_b128 v[20:23], v94 offset:41984
	ds_read_b128 v[28:31], v94 offset:25600
	s_waitcnt lgkmcnt(6)
	v_pk_mul_f32 v[16:17], v[8:9], v[16:17]
	v_pk_mul_f32 v[118:119], v[8:9], v[118:119]
	v_pk_fma_f32 v[16:17], v[10:11], v[18:19], v[16:17]
	v_pk_fma_f32 v[118:119], v[10:11], v[120:121], v[118:119]
	v_add_f32_e32 v16, v16, v17
	v_add_f32_e32 v118, v118, v119
	s_waitcnt lgkmcnt(4)
	v_pk_mul_f32 v[12:13], v[12:13], v[74:75] op_sel_hi:[1,0]
	v_pk_mul_f32 v[14:15], v[14:15], v[74:75] op_sel_hi:[1,0]
	v_add_f32_dpp v16, v16, v16 quad_perm:[1,0,3,2] row_mask:0xf bank_mask:0xf bound_ctrl:1
	v_add_f32_dpp v118, v118, v118 quad_perm:[1,0,3,2] row_mask:0xf bank_mask:0xf bound_ctrl:1
	s_waitcnt lgkmcnt(3)
	v_pk_fma_f32 v[12:13], v[8:9], v[24:25], v[12:13]
	v_pk_fma_f32 v[14:15], v[10:11], v[26:27], v[14:15]
	v_add_f32_dpp v16, v16, v16 quad_perm:[2,3,0,1] row_mask:0xf bank_mask:0xf bound_ctrl:1
	v_add_f32_dpp v118, v118, v118 quad_perm:[2,3,0,1] row_mask:0xf bank_mask:0xf bound_ctrl:1
	ds_read_b128 v[84:87], v94 offset:38144
	ds_read_b128 v[80:83], v94 offset:34048
	v_add_f32_dpp v16, v16, v16 row_half_mirror row_mask:0xf bank_mask:0xf bound_ctrl:1
	v_add_f32_dpp v118, v118, v118 row_half_mirror row_mask:0xf bank_mask:0xf bound_ctrl:1
	ds_read_b32 v88, v39 offset:46336
	ds_read_b128 v[114:117], v94 offset:29952
	v_add_f32_dpp v16, v16, v16 row_mirror row_mask:0xf bank_mask:0xf bound_ctrl:1
	v_add_f32_dpp v118, v118, v118 row_mirror row_mask:0xf bank_mask:0xf bound_ctrl:1
	v_cmp_eq_u32_e32 vcc, 3, v177
	v_and_b32_e32 v79, 0xffff0000, v47
	v_lshlrev_b32_e32 v78, 16, v47
	ds_write_b128 v103, v[76:79] offset:16384
	v_and_b32_e32 v77, 0xffff0000, v48
	v_lshlrev_b32_e32 v76, 16, v48
	v_and_b32_e32 v79, 0xffff0000, v49
	s_waitcnt lgkmcnt(6)
	v_pk_fma_f32 v[8:9], v[20:21], v[16:17], v[12:13] op_sel_hi:[1,0,1] neg_lo:[0,1,0] neg_hi:[0,1,0]
	v_pk_fma_f32 v[10:11], v[22:23], v[16:17], v[14:15] op_sel_hi:[1,0,1] neg_lo:[0,1,0] neg_hi:[0,1,0]
	v_cndmask_b32_e32 v67, v67, v118, vcc
	ds_read_b128 v[110:113], v94 offset:42240
	ds_read_b128 v[118:121], v94 offset:25856
	s_waitcnt lgkmcnt(6)
	v_pk_mul_f32 v[84:85], v[8:9], v[84:85]
	v_pk_mul_f32 v[28:29], v[8:9], v[28:29]
	v_pk_fma_f32 v[84:85], v[10:11], v[86:87], v[84:85]
	v_pk_fma_f32 v[28:29], v[10:11], v[30:31], v[28:29]
	v_add_f32_e32 v84, v84, v85
	v_add_f32_e32 v28, v28, v29
	s_waitcnt lgkmcnt(4)
	v_pk_mul_f32 v[80:81], v[80:81], v[88:89] op_sel_hi:[1,0]
	v_pk_mul_f32 v[82:83], v[82:83], v[88:89] op_sel_hi:[1,0]
	v_add_f32_dpp v84, v84, v84 quad_perm:[1,0,3,2] row_mask:0xf bank_mask:0xf bound_ctrl:1
	v_add_f32_dpp v28, v28, v28 quad_perm:[1,0,3,2] row_mask:0xf bank_mask:0xf bound_ctrl:1
	s_waitcnt lgkmcnt(3)
	v_pk_fma_f32 v[80:81], v[8:9], v[114:115], v[80:81]
	v_pk_fma_f32 v[82:83], v[10:11], v[116:117], v[82:83]
	v_add_f32_dpp v84, v84, v84 quad_perm:[2,3,0,1] row_mask:0xf bank_mask:0xf bound_ctrl:1
	v_add_f32_dpp v28, v28, v28 quad_perm:[2,3,0,1] row_mask:0xf bank_mask:0xf bound_ctrl:1
	ds_read_b128 v[16:19], v94 offset:38400
	ds_read_b128 v[12:15], v94 offset:34304
	v_add_f32_dpp v84, v84, v84 row_half_mirror row_mask:0xf bank_mask:0xf bound_ctrl:1
	v_add_f32_dpp v28, v28, v28 row_half_mirror row_mask:0xf bank_mask:0xf bound_ctrl:1
	ds_read_b32 v74, v39 offset:46592
	ds_read_b128 v[24:27], v94 offset:30208
	v_add_f32_dpp v84, v84, v84 row_mirror row_mask:0xf bank_mask:0xf bound_ctrl:1
	v_add_f32_dpp v28, v28, v28 row_mirror row_mask:0xf bank_mask:0xf bound_ctrl:1
	v_cmp_eq_u32_e32 vcc, 4, v177
	v_lshlrev_b32_e32 v78, 16, v49
	ds_write_b128 v103, v[76:79] offset:20480
	ds_write_b128 v103, v[0:3] offset:4096
	s_add_i32 s6, s88, 4
	s_add_i32 s7, s89, -1
	s_min_u32 s6, s6, s7
	s_waitcnt lgkmcnt(7)
	v_pk_fma_f32 v[8:9], v[110:111], v[84:85], v[80:81] op_sel_hi:[1,0,1] neg_lo:[0,1,0] neg_hi:[0,1,0]
	v_pk_fma_f32 v[10:11], v[112:113], v[84:85], v[82:83] op_sel_hi:[1,0,1] neg_lo:[0,1,0] neg_hi:[0,1,0]
	v_cndmask_b32_e32 v67, v67, v28, vcc
	ds_read_b128 v[20:23], v94 offset:42496
	ds_read_b128 v[28:31], v94 offset:26112
	s_waitcnt lgkmcnt(7)
	v_pk_mul_f32 v[16:17], v[8:9], v[16:17]
	v_pk_mul_f32 v[118:119], v[8:9], v[118:119]
	v_pk_fma_f32 v[16:17], v[10:11], v[18:19], v[16:17]
	v_pk_fma_f32 v[118:119], v[10:11], v[120:121], v[118:119]
	v_add_f32_e32 v16, v16, v17
	v_add_f32_e32 v118, v118, v119
	s_waitcnt lgkmcnt(5)
	v_pk_mul_f32 v[12:13], v[12:13], v[74:75] op_sel_hi:[1,0]
	v_pk_mul_f32 v[14:15], v[14:15], v[74:75] op_sel_hi:[1,0]
	v_add_f32_dpp v16, v16, v16 quad_perm:[1,0,3,2] row_mask:0xf bank_mask:0xf bound_ctrl:1
	v_add_f32_dpp v118, v118, v118 quad_perm:[1,0,3,2] row_mask:0xf bank_mask:0xf bound_ctrl:1
	s_waitcnt lgkmcnt(4)
	v_pk_fma_f32 v[12:13], v[8:9], v[24:25], v[12:13]
	v_pk_fma_f32 v[14:15], v[10:11], v[26:27], v[14:15]
	v_add_f32_dpp v16, v16, v16 quad_perm:[2,3,0,1] row_mask:0xf bank_mask:0xf bound_ctrl:1
	v_add_f32_dpp v118, v118, v118 quad_perm:[2,3,0,1] row_mask:0xf bank_mask:0xf bound_ctrl:1
	ds_read_b128 v[84:87], v94 offset:38656
	ds_read_b128 v[80:83], v94 offset:34560
	v_add_f32_dpp v16, v16, v16 row_half_mirror row_mask:0xf bank_mask:0xf bound_ctrl:1
	v_add_f32_dpp v118, v118, v118 row_half_mirror row_mask:0xf bank_mask:0xf bound_ctrl:1
	ds_read_b32 v88, v39 offset:46848
	ds_read_b128 v[114:117], v94 offset:30464
	v_add_f32_dpp v16, v16, v16 row_mirror row_mask:0xf bank_mask:0xf bound_ctrl:1
	v_add_f32_dpp v118, v118, v118 row_mirror row_mask:0xf bank_mask:0xf bound_ctrl:1
	v_cmp_eq_u32_e32 vcc, 5, v177
	v_lshl_add_u32 v122, s6, 4, v38
	v_ashrrev_i32_e32 v123, 31, v122
	v_lshlrev_b64 v[122:123], 10, v[122:123]
	v_or_b32_e32 v123, v123, v35
	v_or_b32_e32 v122, v122, v52
	v_lshlrev_b64 v[124:125], 1, v[122:123]
	s_waitcnt lgkmcnt(5)
	v_pk_fma_f32 v[8:9], v[20:21], v[16:17], v[12:13] op_sel_hi:[1,0,1] neg_lo:[0,1,0] neg_hi:[0,1,0]
	v_pk_fma_f32 v[10:11], v[22:23], v[16:17], v[14:15] op_sel_hi:[1,0,1] neg_lo:[0,1,0] neg_hi:[0,1,0]
	v_cndmask_b32_e32 v67, v67, v118, vcc
	ds_read_b128 v[110:113], v94 offset:42752
	ds_read_b128 v[118:121], v94 offset:26368
	s_waitcnt lgkmcnt(5)
	v_pk_mul_f32 v[84:85], v[8:9], v[84:85]
	v_pk_mul_f32 v[28:29], v[8:9], v[28:29]
	v_pk_fma_f32 v[84:85], v[10:11], v[86:87], v[84:85]
	v_pk_fma_f32 v[28:29], v[10:11], v[30:31], v[28:29]
	v_add_f32_e32 v84, v84, v85
	v_add_f32_e32 v28, v28, v29
	s_waitcnt lgkmcnt(3)
	v_pk_mul_f32 v[80:81], v[80:81], v[88:89] op_sel_hi:[1,0]
	v_pk_mul_f32 v[82:83], v[82:83], v[88:89] op_sel_hi:[1,0]
	v_add_f32_dpp v84, v84, v84 quad_perm:[1,0,3,2] row_mask:0xf bank_mask:0xf bound_ctrl:1
	v_add_f32_dpp v28, v28, v28 quad_perm:[1,0,3,2] row_mask:0xf bank_mask:0xf bound_ctrl:1
	s_waitcnt lgkmcnt(2)
	v_pk_fma_f32 v[80:81], v[8:9], v[114:115], v[80:81]
	v_pk_fma_f32 v[82:83], v[10:11], v[116:117], v[82:83]
	v_add_f32_dpp v84, v84, v84 quad_perm:[2,3,0,1] row_mask:0xf bank_mask:0xf bound_ctrl:1
	v_add_f32_dpp v28, v28, v28 quad_perm:[2,3,0,1] row_mask:0xf bank_mask:0xf bound_ctrl:1
	ds_read_b128 v[16:19], v94 offset:38912
	ds_read_b128 v[12:15], v94 offset:34816
	v_add_f32_dpp v84, v84, v84 row_half_mirror row_mask:0xf bank_mask:0xf bound_ctrl:1
	v_add_f32_dpp v28, v28, v28 row_half_mirror row_mask:0xf bank_mask:0xf bound_ctrl:1
	ds_read_b32 v74, v39 offset:47104
	ds_read_b128 v[24:27], v94 offset:30720
	v_add_f32_dpp v84, v84, v84 row_mirror row_mask:0xf bank_mask:0xf bound_ctrl:1
	v_add_f32_dpp v28, v28, v28 row_mirror row_mask:0xf bank_mask:0xf bound_ctrl:1
	v_cmp_eq_u32_e32 vcc, 6, v177
	v_lshl_add_u64 v[126:127], s[8:9], 0, v[124:125]
	global_load_dwordx2 v[40:41], v[126:127], off
	v_lshl_add_u64 v[128:129], s[10:11], 0, v[124:125]
	global_load_dwordx2 v[42:43], v[128:129], off
	v_lshl_add_u64 v[130:131], s[12:13], 0, v[124:125]
	global_load_dwordx2 v[44:45], v[130:131], off
	s_waitcnt lgkmcnt(5)
	v_pk_fma_f32 v[8:9], v[110:111], v[84:85], v[80:81] op_sel_hi:[1,0,1] neg_lo:[0,1,0] neg_hi:[0,1,0]
	v_pk_fma_f32 v[10:11], v[112:113], v[84:85], v[82:83] op_sel_hi:[1,0,1] neg_lo:[0,1,0] neg_hi:[0,1,0]
	v_cndmask_b32_e32 v67, v67, v28, vcc
	ds_read_b128 v[20:23], v94 offset:43008
	ds_read_b128 v[28:31], v94 offset:26624
	s_waitcnt lgkmcnt(5)
	v_pk_mul_f32 v[16:17], v[8:9], v[16:17]
	v_pk_mul_f32 v[118:119], v[8:9], v[118:119]
	v_pk_fma_f32 v[16:17], v[10:11], v[18:19], v[16:17]
	v_pk_fma_f32 v[118:119], v[10:11], v[120:121], v[118:119]
	v_add_f32_e32 v16, v16, v17
	v_add_f32_e32 v118, v118, v119
	s_waitcnt lgkmcnt(3)
	v_pk_mul_f32 v[12:13], v[12:13], v[74:75] op_sel_hi:[1,0]
	v_pk_mul_f32 v[14:15], v[14:15], v[74:75] op_sel_hi:[1,0]
	v_add_f32_dpp v16, v16, v16 quad_perm:[1,0,3,2] row_mask:0xf bank_mask:0xf bound_ctrl:1
	v_add_f32_dpp v118, v118, v118 quad_perm:[1,0,3,2] row_mask:0xf bank_mask:0xf bound_ctrl:1
	s_waitcnt lgkmcnt(2)
	v_pk_fma_f32 v[12:13], v[8:9], v[24:25], v[12:13]
	v_pk_fma_f32 v[14:15], v[10:11], v[26:27], v[14:15]
	v_add_f32_dpp v16, v16, v16 quad_perm:[2,3,0,1] row_mask:0xf bank_mask:0xf bound_ctrl:1
	v_add_f32_dpp v118, v118, v118 quad_perm:[2,3,0,1] row_mask:0xf bank_mask:0xf bound_ctrl:1
	ds_read_b128 v[84:87], v94 offset:39168
	ds_read_b128 v[80:83], v94 offset:35072
	v_add_f32_dpp v16, v16, v16 row_half_mirror row_mask:0xf bank_mask:0xf bound_ctrl:1
	v_add_f32_dpp v118, v118, v118 row_half_mirror row_mask:0xf bank_mask:0xf bound_ctrl:1
	ds_read_b32 v88, v39 offset:47360
	ds_read_b128 v[114:117], v94 offset:30976
	v_add_f32_dpp v16, v16, v16 row_mirror row_mask:0xf bank_mask:0xf bound_ctrl:1
	v_add_f32_dpp v118, v118, v118 row_mirror row_mask:0xf bank_mask:0xf bound_ctrl:1
	v_cmp_eq_u32_e32 vcc, 7, v177
	v_lshl_add_u64 v[132:133], s[14:15], 0, v[124:125]
	global_load_dwordx2 v[46:47], v[132:133], off
	v_lshl_add_u64 v[124:125], s[34:35], 0, v[124:125]
	global_load_dwordx2 v[48:49], v[124:125], off
	v_lshl_add_u64 v[122:123], v[122:123], 2, s[36:37]
	global_load_dwordx4 v[0:3], v[122:123], off
	s_waitcnt lgkmcnt(5)
	v_pk_fma_f32 v[8:9], v[20:21], v[16:17], v[12:13] op_sel_hi:[1,0,1] neg_lo:[0,1,0] neg_hi:[0,1,0]
	v_pk_fma_f32 v[10:11], v[22:23], v[16:17], v[14:15] op_sel_hi:[1,0,1] neg_lo:[0,1,0] neg_hi:[0,1,0]
	v_cndmask_b32_e32 v67, v67, v118, vcc
	ds_read_b128 v[110:113], v94 offset:43264
	ds_read_b128 v[118:121], v94 offset:26880
	s_waitcnt lgkmcnt(5)
	v_pk_mul_f32 v[84:85], v[8:9], v[84:85]
	v_pk_mul_f32 v[28:29], v[8:9], v[28:29]
	v_pk_fma_f32 v[84:85], v[10:11], v[86:87], v[84:85]
	v_pk_fma_f32 v[28:29], v[10:11], v[30:31], v[28:29]
	v_add_f32_e32 v84, v84, v85
	v_add_f32_e32 v28, v28, v29
	s_waitcnt lgkmcnt(3)
	v_pk_mul_f32 v[80:81], v[80:81], v[88:89] op_sel_hi:[1,0]
	v_pk_mul_f32 v[82:83], v[82:83], v[88:89] op_sel_hi:[1,0]
	v_add_f32_dpp v84, v84, v84 quad_perm:[1,0,3,2] row_mask:0xf bank_mask:0xf bound_ctrl:1
	v_add_f32_dpp v28, v28, v28 quad_perm:[1,0,3,2] row_mask:0xf bank_mask:0xf bound_ctrl:1
	s_waitcnt lgkmcnt(2)
	v_pk_fma_f32 v[80:81], v[8:9], v[114:115], v[80:81]
	v_pk_fma_f32 v[82:83], v[10:11], v[116:117], v[82:83]
	v_add_f32_dpp v84, v84, v84 quad_perm:[2,3,0,1] row_mask:0xf bank_mask:0xf bound_ctrl:1
	v_add_f32_dpp v28, v28, v28 quad_perm:[2,3,0,1] row_mask:0xf bank_mask:0xf bound_ctrl:1
	ds_read_b128 v[16:19], v94 offset:39424
	ds_read_b128 v[12:15], v94 offset:35328
	v_add_f32_dpp v84, v84, v84 row_half_mirror row_mask:0xf bank_mask:0xf bound_ctrl:1
	v_add_f32_dpp v28, v28, v28 row_half_mirror row_mask:0xf bank_mask:0xf bound_ctrl:1
	ds_read_b32 v74, v39 offset:47616
	ds_read_b128 v[24:27], v94 offset:31232
	v_add_f32_dpp v84, v84, v84 row_mirror row_mask:0xf bank_mask:0xf bound_ctrl:1
	v_add_f32_dpp v28, v28, v28 row_mirror row_mask:0xf bank_mask:0xf bound_ctrl:1
	v_cmp_eq_u32_e32 vcc, 8, v177
	s_waitcnt lgkmcnt(5)
	v_pk_fma_f32 v[8:9], v[110:111], v[84:85], v[80:81] op_sel_hi:[1,0,1] neg_lo:[0,1,0] neg_hi:[0,1,0]
	v_pk_fma_f32 v[10:11], v[112:113], v[84:85], v[82:83] op_sel_hi:[1,0,1] neg_lo:[0,1,0] neg_hi:[0,1,0]
	v_cndmask_b32_e32 v67, v67, v28, vcc
	ds_read_b128 v[20:23], v94 offset:43520
	ds_read_b128 v[28:31], v94 offset:27136
	s_waitcnt lgkmcnt(5)
	v_pk_mul_f32 v[16:17], v[8:9], v[16:17]
	v_pk_mul_f32 v[118:119], v[8:9], v[118:119]
	v_pk_fma_f32 v[16:17], v[10:11], v[18:19], v[16:17]
	v_pk_fma_f32 v[118:119], v[10:11], v[120:121], v[118:119]
	v_add_f32_e32 v16, v16, v17
	v_add_f32_e32 v118, v118, v119
	s_waitcnt lgkmcnt(3)
	v_pk_mul_f32 v[12:13], v[12:13], v[74:75] op_sel_hi:[1,0]
	v_pk_mul_f32 v[14:15], v[14:15], v[74:75] op_sel_hi:[1,0]
	v_add_f32_dpp v16, v16, v16 quad_perm:[1,0,3,2] row_mask:0xf bank_mask:0xf bound_ctrl:1
	v_add_f32_dpp v118, v118, v118 quad_perm:[1,0,3,2] row_mask:0xf bank_mask:0xf bound_ctrl:1
	s_waitcnt lgkmcnt(2)
	v_pk_fma_f32 v[12:13], v[8:9], v[24:25], v[12:13]
	v_pk_fma_f32 v[14:15], v[10:11], v[26:27], v[14:15]
	v_add_f32_dpp v16, v16, v16 quad_perm:[2,3,0,1] row_mask:0xf bank_mask:0xf bound_ctrl:1
	v_add_f32_dpp v118, v118, v118 quad_perm:[2,3,0,1] row_mask:0xf bank_mask:0xf bound_ctrl:1
	ds_read_b128 v[84:87], v94 offset:39680
	ds_read_b128 v[80:83], v94 offset:35584
	v_add_f32_dpp v16, v16, v16 row_half_mirror row_mask:0xf bank_mask:0xf bound_ctrl:1
	v_add_f32_dpp v118, v118, v118 row_half_mirror row_mask:0xf bank_mask:0xf bound_ctrl:1
	ds_read_b32 v88, v39 offset:47872
	ds_read_b128 v[114:117], v94 offset:31488
	v_add_f32_dpp v16, v16, v16 row_mirror row_mask:0xf bank_mask:0xf bound_ctrl:1
	v_add_f32_dpp v118, v118, v118 row_mirror row_mask:0xf bank_mask:0xf bound_ctrl:1
	v_cmp_eq_u32_e32 vcc, 9, v177
	s_waitcnt lgkmcnt(5)
	v_pk_fma_f32 v[8:9], v[20:21], v[16:17], v[12:13] op_sel_hi:[1,0,1] neg_lo:[0,1,0] neg_hi:[0,1,0]
	v_pk_fma_f32 v[10:11], v[22:23], v[16:17], v[14:15] op_sel_hi:[1,0,1] neg_lo:[0,1,0] neg_hi:[0,1,0]
	v_cndmask_b32_e32 v67, v67, v118, vcc
	ds_read_b128 v[110:113], v94 offset:43776
	ds_read_b128 v[118:121], v94 offset:27392
	s_waitcnt lgkmcnt(5)
	v_pk_mul_f32 v[84:85], v[8:9], v[84:85]
	v_pk_mul_f32 v[28:29], v[8:9], v[28:29]
	v_pk_fma_f32 v[84:85], v[10:11], v[86:87], v[84:85]
	v_pk_fma_f32 v[28:29], v[10:11], v[30:31], v[28:29]
	v_add_f32_e32 v84, v84, v85
	v_add_f32_e32 v28, v28, v29
	s_waitcnt lgkmcnt(3)
	v_pk_mul_f32 v[80:81], v[80:81], v[88:89] op_sel_hi:[1,0]
	v_pk_mul_f32 v[82:83], v[82:83], v[88:89] op_sel_hi:[1,0]
	v_add_f32_dpp v84, v84, v84 quad_perm:[1,0,3,2] row_mask:0xf bank_mask:0xf bound_ctrl:1
	v_add_f32_dpp v28, v28, v28 quad_perm:[1,0,3,2] row_mask:0xf bank_mask:0xf bound_ctrl:1
	s_waitcnt lgkmcnt(2)
	v_pk_fma_f32 v[80:81], v[8:9], v[114:115], v[80:81]
	v_pk_fma_f32 v[82:83], v[10:11], v[116:117], v[82:83]
	v_add_f32_dpp v84, v84, v84 quad_perm:[2,3,0,1] row_mask:0xf bank_mask:0xf bound_ctrl:1
	v_add_f32_dpp v28, v28, v28 quad_perm:[2,3,0,1] row_mask:0xf bank_mask:0xf bound_ctrl:1
	ds_read_b128 v[16:19], v94 offset:39936
	ds_read_b128 v[12:15], v94 offset:35840
	v_add_f32_dpp v84, v84, v84 row_half_mirror row_mask:0xf bank_mask:0xf bound_ctrl:1
	v_add_f32_dpp v28, v28, v28 row_half_mirror row_mask:0xf bank_mask:0xf bound_ctrl:1
	ds_read_b32 v74, v39 offset:48128
	ds_read_b128 v[24:27], v94 offset:31744
	v_add_f32_dpp v84, v84, v84 row_mirror row_mask:0xf bank_mask:0xf bound_ctrl:1
	v_add_f32_dpp v28, v28, v28 row_mirror row_mask:0xf bank_mask:0xf bound_ctrl:1
	v_cmp_eq_u32_e32 vcc, 10, v177
	s_waitcnt lgkmcnt(5)
	v_pk_fma_f32 v[8:9], v[110:111], v[84:85], v[80:81] op_sel_hi:[1,0,1] neg_lo:[0,1,0] neg_hi:[0,1,0]
	v_pk_fma_f32 v[10:11], v[112:113], v[84:85], v[82:83] op_sel_hi:[1,0,1] neg_lo:[0,1,0] neg_hi:[0,1,0]
	v_cndmask_b32_e32 v67, v67, v28, vcc
	ds_read_b128 v[20:23], v94 offset:44032
	ds_read_b128 v[28:31], v94 offset:27648
	s_waitcnt lgkmcnt(5)
	v_pk_mul_f32 v[16:17], v[8:9], v[16:17]
	v_pk_mul_f32 v[118:119], v[8:9], v[118:119]
	v_pk_fma_f32 v[16:17], v[10:11], v[18:19], v[16:17]
	v_pk_fma_f32 v[118:119], v[10:11], v[120:121], v[118:119]
	v_add_f32_e32 v16, v16, v17
	v_add_f32_e32 v118, v118, v119
	s_waitcnt lgkmcnt(3)
	v_pk_mul_f32 v[12:13], v[12:13], v[74:75] op_sel_hi:[1,0]
	v_pk_mul_f32 v[14:15], v[14:15], v[74:75] op_sel_hi:[1,0]
	v_add_f32_dpp v16, v16, v16 quad_perm:[1,0,3,2] row_mask:0xf bank_mask:0xf bound_ctrl:1
	v_add_f32_dpp v118, v118, v118 quad_perm:[1,0,3,2] row_mask:0xf bank_mask:0xf bound_ctrl:1
	s_waitcnt lgkmcnt(2)
	v_pk_fma_f32 v[12:13], v[8:9], v[24:25], v[12:13]
	v_pk_fma_f32 v[14:15], v[10:11], v[26:27], v[14:15]
	v_add_f32_dpp v16, v16, v16 quad_perm:[2,3,0,1] row_mask:0xf bank_mask:0xf bound_ctrl:1
	v_add_f32_dpp v118, v118, v118 quad_perm:[2,3,0,1] row_mask:0xf bank_mask:0xf bound_ctrl:1
	ds_read_b128 v[84:87], v94 offset:40192
	ds_read_b128 v[80:83], v94 offset:36096
	v_add_f32_dpp v16, v16, v16 row_half_mirror row_mask:0xf bank_mask:0xf bound_ctrl:1
	v_add_f32_dpp v118, v118, v118 row_half_mirror row_mask:0xf bank_mask:0xf bound_ctrl:1
	ds_read_b32 v88, v39 offset:48384
	ds_read_b128 v[114:117], v94 offset:32000
	v_add_f32_dpp v16, v16, v16 row_mirror row_mask:0xf bank_mask:0xf bound_ctrl:1
	v_add_f32_dpp v118, v118, v118 row_mirror row_mask:0xf bank_mask:0xf bound_ctrl:1
	v_cmp_eq_u32_e32 vcc, 11, v177
	s_waitcnt lgkmcnt(5)
	v_pk_fma_f32 v[8:9], v[20:21], v[16:17], v[12:13] op_sel_hi:[1,0,1] neg_lo:[0,1,0] neg_hi:[0,1,0]
	v_pk_fma_f32 v[10:11], v[22:23], v[16:17], v[14:15] op_sel_hi:[1,0,1] neg_lo:[0,1,0] neg_hi:[0,1,0]
	v_cndmask_b32_e32 v67, v67, v118, vcc
	ds_read_b128 v[110:113], v94 offset:44288
	ds_read_b128 v[118:121], v94 offset:27904
	s_waitcnt lgkmcnt(5)
	v_pk_mul_f32 v[84:85], v[8:9], v[84:85]
	v_pk_mul_f32 v[28:29], v[8:9], v[28:29]
	v_pk_fma_f32 v[84:85], v[10:11], v[86:87], v[84:85]
	v_pk_fma_f32 v[28:29], v[10:11], v[30:31], v[28:29]
	v_add_f32_e32 v84, v84, v85
	v_add_f32_e32 v28, v28, v29
	s_waitcnt lgkmcnt(3)
	v_pk_mul_f32 v[80:81], v[80:81], v[88:89] op_sel_hi:[1,0]
	v_pk_mul_f32 v[82:83], v[82:83], v[88:89] op_sel_hi:[1,0]
	v_add_f32_dpp v84, v84, v84 quad_perm:[1,0,3,2] row_mask:0xf bank_mask:0xf bound_ctrl:1
	v_add_f32_dpp v28, v28, v28 quad_perm:[1,0,3,2] row_mask:0xf bank_mask:0xf bound_ctrl:1
	s_waitcnt lgkmcnt(2)
	v_pk_fma_f32 v[80:81], v[8:9], v[114:115], v[80:81]
	v_pk_fma_f32 v[82:83], v[10:11], v[116:117], v[82:83]
	v_add_f32_dpp v84, v84, v84 quad_perm:[2,3,0,1] row_mask:0xf bank_mask:0xf bound_ctrl:1
	v_add_f32_dpp v28, v28, v28 quad_perm:[2,3,0,1] row_mask:0xf bank_mask:0xf bound_ctrl:1
	ds_read_b128 v[16:19], v94 offset:40448
	ds_read_b128 v[12:15], v94 offset:36352
	v_add_f32_dpp v84, v84, v84 row_half_mirror row_mask:0xf bank_mask:0xf bound_ctrl:1
	v_add_f32_dpp v28, v28, v28 row_half_mirror row_mask:0xf bank_mask:0xf bound_ctrl:1
	ds_read_b32 v74, v39 offset:48640
	ds_read_b128 v[24:27], v94 offset:32256
	v_add_f32_dpp v84, v84, v84 row_mirror row_mask:0xf bank_mask:0xf bound_ctrl:1
	v_add_f32_dpp v28, v28, v28 row_mirror row_mask:0xf bank_mask:0xf bound_ctrl:1
	v_cmp_eq_u32_e32 vcc, 12, v177
	s_waitcnt lgkmcnt(5)
	v_pk_fma_f32 v[8:9], v[110:111], v[84:85], v[80:81] op_sel_hi:[1,0,1] neg_lo:[0,1,0] neg_hi:[0,1,0]
	v_pk_fma_f32 v[10:11], v[112:113], v[84:85], v[82:83] op_sel_hi:[1,0,1] neg_lo:[0,1,0] neg_hi:[0,1,0]
	v_cndmask_b32_e32 v67, v67, v28, vcc
	ds_read_b128 v[20:23], v94 offset:44544
	ds_read_b128 v[28:31], v94 offset:28160
	s_waitcnt lgkmcnt(5)
	v_pk_mul_f32 v[16:17], v[8:9], v[16:17]
	v_pk_mul_f32 v[118:119], v[8:9], v[118:119]
	v_pk_fma_f32 v[16:17], v[10:11], v[18:19], v[16:17]
	v_pk_fma_f32 v[118:119], v[10:11], v[120:121], v[118:119]
	v_add_f32_e32 v16, v16, v17
	v_add_f32_e32 v118, v118, v119
	s_waitcnt lgkmcnt(3)
	v_pk_mul_f32 v[12:13], v[12:13], v[74:75] op_sel_hi:[1,0]
	v_pk_mul_f32 v[14:15], v[14:15], v[74:75] op_sel_hi:[1,0]
	v_add_f32_dpp v16, v16, v16 quad_perm:[1,0,3,2] row_mask:0xf bank_mask:0xf bound_ctrl:1
	v_add_f32_dpp v118, v118, v118 quad_perm:[1,0,3,2] row_mask:0xf bank_mask:0xf bound_ctrl:1
	s_waitcnt lgkmcnt(2)
	v_pk_fma_f32 v[12:13], v[8:9], v[24:25], v[12:13]
	v_pk_fma_f32 v[14:15], v[10:11], v[26:27], v[14:15]
	v_add_f32_dpp v16, v16, v16 quad_perm:[2,3,0,1] row_mask:0xf bank_mask:0xf bound_ctrl:1
	v_add_f32_dpp v118, v118, v118 quad_perm:[2,3,0,1] row_mask:0xf bank_mask:0xf bound_ctrl:1
	ds_read_b128 v[84:87], v94 offset:40704
	ds_read_b128 v[80:83], v94 offset:36608
	v_add_f32_dpp v16, v16, v16 row_half_mirror row_mask:0xf bank_mask:0xf bound_ctrl:1
	v_add_f32_dpp v118, v118, v118 row_half_mirror row_mask:0xf bank_mask:0xf bound_ctrl:1
	ds_read_b32 v88, v39 offset:48896
	ds_read_b128 v[114:117], v94 offset:32512
	v_add_f32_dpp v16, v16, v16 row_mirror row_mask:0xf bank_mask:0xf bound_ctrl:1
	v_add_f32_dpp v118, v118, v118 row_mirror row_mask:0xf bank_mask:0xf bound_ctrl:1
	v_cmp_eq_u32_e32 vcc, 13, v177
	s_waitcnt lgkmcnt(5)
	v_pk_fma_f32 v[8:9], v[20:21], v[16:17], v[12:13] op_sel_hi:[1,0,1] neg_lo:[0,1,0] neg_hi:[0,1,0]
	v_pk_fma_f32 v[10:11], v[22:23], v[16:17], v[14:15] op_sel_hi:[1,0,1] neg_lo:[0,1,0] neg_hi:[0,1,0]
	v_cndmask_b32_e32 v67, v67, v118, vcc
	ds_read_b128 v[110:113], v94 offset:44800
	ds_read_b128 v[118:121], v94 offset:28416
	s_waitcnt lgkmcnt(5)
	v_pk_mul_f32 v[84:85], v[8:9], v[84:85]
	v_pk_mul_f32 v[28:29], v[8:9], v[28:29]
	v_pk_fma_f32 v[84:85], v[10:11], v[86:87], v[84:85]
	v_pk_fma_f32 v[28:29], v[10:11], v[30:31], v[28:29]
	v_add_f32_e32 v84, v84, v85
	v_add_f32_e32 v28, v28, v29
	s_waitcnt lgkmcnt(3)
	v_pk_mul_f32 v[80:81], v[80:81], v[88:89] op_sel_hi:[1,0]
	v_pk_mul_f32 v[82:83], v[82:83], v[88:89] op_sel_hi:[1,0]
	v_add_f32_dpp v84, v84, v84 quad_perm:[1,0,3,2] row_mask:0xf bank_mask:0xf bound_ctrl:1
	v_add_f32_dpp v28, v28, v28 quad_perm:[1,0,3,2] row_mask:0xf bank_mask:0xf bound_ctrl:1
	s_waitcnt lgkmcnt(2)
	v_pk_fma_f32 v[80:81], v[8:9], v[114:115], v[80:81]
	v_pk_fma_f32 v[82:83], v[10:11], v[116:117], v[82:83]
	v_add_f32_dpp v84, v84, v84 quad_perm:[2,3,0,1] row_mask:0xf bank_mask:0xf bound_ctrl:1
	v_add_f32_dpp v28, v28, v28 quad_perm:[2,3,0,1] row_mask:0xf bank_mask:0xf bound_ctrl:1
	s_nop 1
	v_add_f32_dpp v84, v84, v84 row_half_mirror row_mask:0xf bank_mask:0xf bound_ctrl:1
	v_add_f32_dpp v28, v28, v28 row_half_mirror row_mask:0xf bank_mask:0xf bound_ctrl:1
	s_nop 1
	v_add_f32_dpp v84, v84, v84 row_mirror row_mask:0xf bank_mask:0xf bound_ctrl:1
	v_add_f32_dpp v28, v28, v28 row_mirror row_mask:0xf bank_mask:0xf bound_ctrl:1
	v_cmp_eq_u32_e32 vcc, 14, v177
	s_waitcnt lgkmcnt(1)
	v_pk_fma_f32 v[8:9], v[110:111], v[84:85], v[80:81] op_sel_hi:[1,0,1] neg_lo:[0,1,0] neg_hi:[0,1,0]
	v_pk_fma_f32 v[10:11], v[112:113], v[84:85], v[82:83] op_sel_hi:[1,0,1] neg_lo:[0,1,0] neg_hi:[0,1,0]
	v_cndmask_b32_e32 v67, v67, v28, vcc
	s_waitcnt lgkmcnt(0)
	v_pk_mul_f32 v[118:119], v[8:9], v[118:119]
	s_nop 0
	v_pk_fma_f32 v[118:119], v[10:11], v[120:121], v[118:119]
	s_add_i32 s6, s88, 1
	v_add_f32_e32 v118, v118, v119
	v_lshl_add_u32 v78, s6, 4, v178
	v_ashrrev_i32_e32 v79, 31, v78
	v_add_f32_dpp v118, v118, v118 quad_perm:[1,0,3,2] row_mask:0xf bank_mask:0xf bound_ctrl:1
	v_lshlrev_b64 v[78:79], 11, v[78:79]
	v_cmp_eq_u32_e32 vcc, 15, v177
	v_add_f32_dpp v118, v118, v118 quad_perm:[2,3,0,1] row_mask:0xf bank_mask:0xf bound_ctrl:1
	v_lshl_add_u64 v[78:79], v[180:181], 0, v[78:79]
	s_nop 0
	v_add_f32_dpp v118, v118, v118 row_half_mirror row_mask:0xf bank_mask:0xf bound_ctrl:1
	s_nop 1
	v_add_f32_dpp v118, v118, v118 row_mirror row_mask:0xf bank_mask:0xf bound_ctrl:1
	s_nop 0
	v_cndmask_b32_e32 v67, v67, v118, vcc
	v_bfe_u32 v76, v67, 16, 1
	v_add3_u32 v76, v67, v76, s33
	global_store_short_d16_hi v[78:79], v76, off
	s_waitcnt lgkmcnt(0)
	s_barrier
	s_add_i32 s88, s88, 2
	s_cmp_lt_u32 s88, s89
	s_cbranch_scc1 .Lscan_tiles
.Lscan_tiles_done:
	s_waitcnt vmcnt(0)
